# speedup vs baseline: 1.0013x; 1.0013x over previous
; #define G_STAGE(bufoff, gbase, voff) do { _Pragma("unroll") for (int _i = 0; _i < 2; ++_i) \
;         __builtin_amdgcn_global_load_lds((const unsigned*)((const char*)(gbase) + (voff)[_i]), (LAS unsigned*)(lds + (bufoff) + ldsw + _i * 8192), 16, 0, 0); } while (0)
; #define G_LDA(dst, b, h) do { _Pragma("unroll") for (int m = 0; m < 4; ++m) _Pragma("unroll") for (int k = 0; k < 2; ++k) dst[m][k] = *(const LAS bf16x8*)(lds + G_SA(b, h) + aoff + m * 2048 + k * 1024); } while (0)
; #define G_LDB(dst, b, h) do { _Pragma("unroll") for (int n = 0; n < 2; ++n) _Pragma("unroll") for (int k = 0; k < 2; ++k) dst[n][k] = *(const LAS bf16x8*)(lds + G_SB(b, h) + boff + n * 2048 + k * 1024); } while (0)
; #define G_MMA(ai, bj, At, Bt) do { __builtin_amdgcn_s_setprio(1); _Pragma("unroll") for (int m = 0; m < 4; ++m) _Pragma("unroll") for (int n = 0; n < 2; ++n) _Pragma("unroll") for (int k = 0; k < 2; ++k) \
;         acc[ai][bj][m][n] = __builtin_amdgcn_mfma_f32_16x16x32_bf16(Bt[n][k], At[m][k], acc[ai][bj][m][n], 0, 0, 0); __builtin_amdgcn_s_setprio(0); } while (0)
; #define G_WAIT_L(n) asm volatile("s_waitcnt lgkmcnt(" #n ")" ::: "memory")
; #define G_BAR __builtin_amdgcn_s_barrier()
; #define G_SCHED __builtin_amdgcn_sched_barrier(0)
; template <class J>
; DI void gemm_phase(LAS unsigned char* lds, const J& job) {
;     ...
;     for (int t = 0; t < nt; t += 2) {
;       const bool last = (t == nt - 2);
;       const char* a1 = cA + G_KT(t + 1);
;       const char* a2 = last ? nA + G_KT(0) : cA + G_KT(t + 2); const char* b2 = last ? nB + G_KT(0) : cB + G_KT(t + 2);
;       const char* a3 = last ? nA + G_KT(1) : cA + G_KT(t + 3); const char* b3 = last ? nB + G_KT(1) : cB + G_KT(t + 3);
;       G_LDB(B0, 0, 0); G_SCHED; G_LDA(At, 0, 0); G_STAGE(G_SA(1, 1), a1 + hstepA, voffA);
;       G_WAIT_L(8); G_BAR; G_WAIT_L(0); G_MMA(0, 0, At, B0); G_BAR; G_SCHED;
;       G_LDB(B1, 0, 1); G_STAGE(G_SB(0, 0), b2, voffB);
;       G_BAR; G_WAIT_L(0); G_MMA(0, 1, At, B1); G_BAR;
;       G_LDA(At, 0, 1); G_STAGE(G_SA(0, 0), a2, voffA);
;       G_BAR; G_WAIT_L(0); G_MMA(1, 0, At, B0); G_BAR; G_SCHED;
.LBB0_42:
	s_add_i32 s1, s57, 0xffffff80
	s_and_b32 s0, s44, 0xf80
	s_and_b32 s1, s1, 0xf00
	s_add_u32 s2, s70, s1
	s_addc_u32 s72, s71, 0
	s_add_u32 s1, s68, s1
	s_addc_u32 s73, s69, 0
	s_and_b32 s74, s57, 0xf80
	s_add_u32 s80, s70, s74
	s_addc_u32 s75, s71, 0
	s_add_u32 s54, s68, s74
	s_addc_u32 s55, s69, 0
	s_cmp_eq_u32 s7, 28
	s_cselect_b32 s77, vcc_lo, s72
	s_cselect_b32 s76, s47, s2
	s_cselect_b32 s79, s33, s73
	s_cselect_b32 s78, vcc_hi, s1
	s_cselect_b32 s75, s4, s75
	s_cselect_b32 s74, s97, s80
	s_cselect_b32 s73, s6, s55
	s_cselect_b32 s72, s5, s54
	s_add_i32 s2, s84, 0x100
	v_add_u32_e32 v140, s2, v162
	ds_read_b128 v[128:131], v140
	ds_read_b128 v[132:135], v140 offset:1024
	ds_read_b128 v[136:139], v140 offset:2048
	ds_read_b128 v[140:143], v140 offset:3072
	s_add_u32 s0, s21, s0
	s_addc_u32 s1, s23, 0
	v_lshl_add_u64 v[158:159], s[0:1], 0, v[148:149]
	s_add_i32 m0, s25, 0xc000
	ds_read_b128 v[154:157], v163
	ds_read_b128 v[164:167], v163 offset:1024
	ds_read_b128 v[168:171], v163 offset:2048
	ds_read_b128 v[172:175], v163 offset:3072
	ds_read_b128 v[176:179], v163 offset:4096
	ds_read_b128 v[180:183], v163 offset:5120
	ds_read_b128 v[184:187], v163 offset:6144
	ds_read_b128 v[188:191], v163 offset:7168
	global_load_lds_dwordx4 v[158:159], off
	v_lshl_add_u64 v[158:159], s[0:1], 0, v[150:151]
	s_add_i32 m0, s25, 0xe000
	s_nop 0
	global_load_lds_dwordx4 v[158:159], off
	s_waitcnt lgkmcnt(8)
	s_barrier
	s_waitcnt lgkmcnt(0)
	s_setprio 1
	s_waitcnt lgkmcnt(0)
	v_mfma_f32_16x16x32_bf16 v[124:127], v[128:131], v[154:157], v[124:127]
	v_mfma_f32_16x16x32_bf16 v[120:123], v[136:139], v[154:157], v[120:123]
	v_mfma_f32_16x16x32_bf16 v[108:111], v[128:131], v[168:171], v[108:111]
	v_mfma_f32_16x16x32_bf16 v[104:107], v[136:139], v[168:171], v[104:107]
	v_mfma_f32_16x16x32_bf16 v[92:95], v[128:131], v[176:179], v[92:95]
	v_mfma_f32_16x16x32_bf16 v[88:91], v[136:139], v[176:179], v[88:91]
	v_mfma_f32_16x16x32_bf16 v[76:79], v[128:131], v[184:187], v[76:79]
	v_mfma_f32_16x16x32_bf16 v[72:75], v[136:139], v[184:187], v[72:75]
	v_mfma_f32_16x16x32_bf16 v[124:127], v[132:135], v[164:167], v[124:127]
	v_mfma_f32_16x16x32_bf16 v[120:123], v[140:143], v[164:167], v[120:123]
	v_mfma_f32_16x16x32_bf16 v[108:111], v[132:135], v[172:175], v[108:111]
	v_mfma_f32_16x16x32_bf16 v[104:107], v[140:143], v[172:175], v[104:107]
	v_mfma_f32_16x16x32_bf16 v[92:95], v[132:135], v[180:183], v[92:95]
	v_mfma_f32_16x16x32_bf16 v[88:91], v[140:143], v[180:183], v[88:91]
	v_mfma_f32_16x16x32_bf16 v[76:79], v[132:135], v[188:191], v[76:79]
	v_mfma_f32_16x16x32_bf16 v[72:75], v[140:143], v[188:191], v[72:75]
	s_setprio 0
	s_barrier
	s_add_i32 s54, s85, 0x100
	v_add_u32_e32 v158, s54, v162
	s_add_i32 s0, s2, s14
	ds_read_b128 v[192:195], v158
	ds_read_b128 v[196:199], v158 offset:1024
	ds_read_b128 v[200:203], v158 offset:2048
	ds_read_b128 v[204:207], v158 offset:3072
	v_lshl_add_u64 v[158:159], s[78:79], 0, v[146:147]
	s_mov_b32 m0, s0
	s_nop 0
	global_load_lds_dwordx4 v[158:159], off
	v_lshl_add_u64 v[158:159], s[78:79], 0, v[152:153]
	s_add_i32 m0, s0, 0x2000
	s_nop 0
	global_load_lds_dwordx4 v[158:159], off
	s_barrier
	s_waitcnt lgkmcnt(0)
	s_setprio 1
	s_waitcnt lgkmcnt(0)
	v_mfma_f32_16x16x32_bf16 v[116:119], v[192:195], v[154:157], v[116:119]
	v_mfma_f32_16x16x32_bf16 v[112:115], v[200:203], v[154:157], v[112:115]
	v_mfma_f32_16x16x32_bf16 v[100:103], v[192:195], v[168:171], v[100:103]
	v_mfma_f32_16x16x32_bf16 v[96:99], v[200:203], v[168:171], v[96:99]
	v_mfma_f32_16x16x32_bf16 v[84:87], v[192:195], v[176:179], v[84:87]
	v_mfma_f32_16x16x32_bf16 v[80:83], v[200:203], v[176:179], v[80:83]
	v_mfma_f32_16x16x32_bf16 v[68:71], v[192:195], v[184:187], v[68:71]
	v_mfma_f32_16x16x32_bf16 v[64:67], v[200:203], v[184:187], v[64:67]
	v_mfma_f32_16x16x32_bf16 v[116:119], v[196:199], v[164:167], v[116:119]
	v_mfma_f32_16x16x32_bf16 v[112:115], v[204:207], v[164:167], v[112:115]
	v_mfma_f32_16x16x32_bf16 v[100:103], v[196:199], v[172:175], v[100:103]
	v_mfma_f32_16x16x32_bf16 v[96:99], v[204:207], v[172:175], v[96:99]
	v_mfma_f32_16x16x32_bf16 v[84:87], v[196:199], v[180:183], v[84:87]
	v_mfma_f32_16x16x32_bf16 v[80:83], v[204:207], v[180:183], v[80:83]
	v_mfma_f32_16x16x32_bf16 v[68:71], v[196:199], v[188:191], v[68:71]
	v_mfma_f32_16x16x32_bf16 v[64:67], v[204:207], v[188:191], v[64:67]
	s_setprio 0
	s_mov_b32 m0, s25
	v_lshl_add_u64 v[158:159], s[76:77], 0, v[148:149]
	s_barrier
	ds_read_b128 v[154:157], v163 offset:16384
	ds_read_b128 v[164:167], v163 offset:17408
	ds_read_b128 v[168:171], v163 offset:18432
	ds_read_b128 v[172:175], v163 offset:19456
	ds_read_b128 v[176:179], v163 offset:20480
	ds_read_b128 v[180:183], v163 offset:21504
	ds_read_b128 v[184:187], v163 offset:22528
	ds_read_b128 v[188:191], v163 offset:23552
	global_load_lds_dwordx4 v[158:159], off
	v_lshl_add_u64 v[158:159], s[76:77], 0, v[150:151]
	s_mov_b32 m0, s36
	s_nop 0
	global_load_lds_dwordx4 v[158:159], off
	s_barrier
	s_waitcnt lgkmcnt(0)
	s_setprio 1
	s_waitcnt lgkmcnt(0)
	v_mfma_f32_16x16x32_bf16 v[60:63], v[128:131], v[154:157], v[60:63]
	v_mfma_f32_16x16x32_bf16 v[56:59], v[136:139], v[154:157], v[56:59]
	v_mfma_f32_16x16x32_bf16 v[44:47], v[128:131], v[168:171], v[44:47]
	v_mfma_f32_16x16x32_bf16 v[40:43], v[136:139], v[168:171], v[40:43]
	v_mfma_f32_16x16x32_bf16 v[28:31], v[128:131], v[176:179], v[28:31]
	v_mfma_f32_16x16x32_bf16 v[24:27], v[136:139], v[176:179], v[24:27]
	v_mfma_f32_16x16x32_bf16 v[20:23], v[128:131], v[184:187], v[20:23]
	v_mfma_f32_16x16x32_bf16 v[12:15], v[136:139], v[184:187], v[12:15]
	v_mfma_f32_16x16x32_bf16 v[60:63], v[132:135], v[164:167], v[60:63]
	v_mfma_f32_16x16x32_bf16 v[56:59], v[140:143], v[164:167], v[56:59]
	v_mfma_f32_16x16x32_bf16 v[44:47], v[132:135], v[172:175], v[44:47]
	v_mfma_f32_16x16x32_bf16 v[40:43], v[140:143], v[172:175], v[40:43]
	v_mfma_f32_16x16x32_bf16 v[28:31], v[132:135], v[180:183], v[28:31]
	v_mfma_f32_16x16x32_bf16 v[24:27], v[140:143], v[180:183], v[24:27]
	v_mfma_f32_16x16x32_bf16 v[20:23], v[132:135], v[188:191], v[20:23]
	v_mfma_f32_16x16x32_bf16 v[12:15], v[140:143], v[188:191], v[12:15]
	s_setprio 0
	s_barrier
; #define G_STAGE(bufoff, gbase, voff) do { _Pragma("unroll") for (int _i = 0; _i < 2; ++_i) \
;         __builtin_amdgcn_global_load_lds((const unsigned*)((const char*)(gbase) + (voff)[_i]), (LAS unsigned*)(lds + (bufoff) + ldsw + _i * 8192), 16, 0, 0); } while (0)
; #define G_LDA(dst, b, h) do { _Pragma("unroll") for (int m = 0; m < 4; ++m) _Pragma("unroll") for (int k = 0; k < 2; ++k) dst[m][k] = *(const LAS bf16x8*)(lds + G_SA(b, h) + aoff + m * 2048 + k * 1024); } while (0)
; #define G_LDB(dst, b, h) do { _Pragma("unroll") for (int n = 0; n < 2; ++n) _Pragma("unroll") for (int k = 0; k < 2; ++k) dst[n][k] = *(const LAS bf16x8*)(lds + G_SB(b, h) + boff + n * 2048 + k * 1024); } while (0)
; #define G_MMA(ai, bj, At, Bt) do { __builtin_amdgcn_s_setprio(1); _Pragma("unroll") for (int m = 0; m < 4; ++m) _Pragma("unroll") for (int n = 0; n < 2; ++n) _Pragma("unroll") for (int k = 0; k < 2; ++k) \
;         acc[ai][bj][m][n] = __builtin_amdgcn_mfma_f32_16x16x32_bf16(Bt[n][k], At[m][k], acc[ai][bj][m][n], 0, 0, 0); __builtin_amdgcn_s_setprio(0); } while (0)
; #define G_WAIT_V(n) asm volatile("s_waitcnt vmcnt(" #n ")" ::: "memory")
; #define G_WAIT_L(n) asm volatile("s_waitcnt lgkmcnt(" #n ")" ::: "memory")
; #define G_BAR __builtin_amdgcn_s_barrier()
; #define G_SCHED __builtin_amdgcn_sched_barrier(0)
; template <class J>
; DI void gemm_phase(LAS unsigned char* lds, const J& job) {
;     ...
;       G_STAGE(G_SB(0, 1), b2 + hstepB, voffB);
;       G_WAIT_V(6); G_BAR; G_MMA(1, 1, At, B1); G_BAR;
;       G_LDB(B0, 1, 0); G_SCHED; G_LDA(At, 1, 0); G_STAGE(G_SA(0, 1), a2 + hstepA, voffA);
;       G_WAIT_L(8); G_BAR; G_WAIT_L(0); G_MMA(0, 0, At, B0); G_BAR; G_SCHED;
;       G_LDB(B1, 1, 1); G_STAGE(G_SB(1, 0), b3, voffB);
;       G_BAR; G_WAIT_L(0); G_MMA(0, 1, At, B1); G_BAR;
;       G_LDA(At, 1, 1); G_STAGE(G_SA(1, 0), a3, voffA);
	s_add_u32 s0, s78, 0x80000
	s_addc_u32 s1, s79, 0
	s_add_i32 s2, s54, s14
	v_lshl_add_u64 v[128:129], s[0:1], 0, v[146:147]
	s_mov_b32 m0, s2
	s_nop 0
	global_load_lds_dwordx4 v[128:129], off
	v_lshl_add_u64 v[128:129], s[0:1], 0, v[152:153]
	s_add_i32 m0, s2, 0x2000
	s_nop 0
	global_load_lds_dwordx4 v[128:129], off
	s_waitcnt vmcnt(6)
	s_barrier
	s_setprio 1
	v_mfma_f32_16x16x32_bf16 v[52:55], v[192:195], v[154:157], v[52:55]
	v_mfma_f32_16x16x32_bf16 v[48:51], v[200:203], v[154:157], v[48:51]
	v_mfma_f32_16x16x32_bf16 v[36:39], v[192:195], v[168:171], v[36:39]
	v_mfma_f32_16x16x32_bf16 v[32:35], v[200:203], v[168:171], v[32:35]
	v_mfma_f32_16x16x32_bf16 v[16:19], v[192:195], v[176:179], v[16:19]
	v_mfma_f32_16x16x32_bf16 v[8:11], v[200:203], v[176:179], v[8:11]
	v_mfma_f32_16x16x32_bf16 v[4:7], v[192:195], v[184:187], v[4:7]
	v_mfma_f32_16x16x32_bf16 v[0:3], v[200:203], v[184:187], v[0:3]
	v_mfma_f32_16x16x32_bf16 v[52:55], v[196:199], v[164:167], v[52:55]
	v_mfma_f32_16x16x32_bf16 v[48:51], v[204:207], v[164:167], v[48:51]
	v_mfma_f32_16x16x32_bf16 v[36:39], v[196:199], v[172:175], v[36:39]
	v_mfma_f32_16x16x32_bf16 v[32:35], v[204:207], v[172:175], v[32:35]
	v_mfma_f32_16x16x32_bf16 v[16:19], v[196:199], v[180:183], v[16:19]
	v_mfma_f32_16x16x32_bf16 v[8:11], v[204:207], v[180:183], v[8:11]
	v_mfma_f32_16x16x32_bf16 v[4:7], v[196:199], v[188:191], v[4:7]
	v_mfma_f32_16x16x32_bf16 v[0:3], v[204:207], v[188:191], v[0:3]
	s_setprio 0
	s_add_i32 s2, s88, 0x100
	v_add_u32_e32 v140, s2, v162
	s_barrier
	ds_read_b128 v[128:131], v140
	ds_read_b128 v[132:135], v140 offset:1024
	ds_read_b128 v[136:139], v140 offset:2048
	ds_read_b128 v[140:143], v140 offset:3072
	s_add_u32 s0, s76, 0x80000
	s_addc_u32 s1, s77, 0
	s_mov_b32 m0, s37
	v_lshl_add_u64 v[158:159], s[0:1], 0, v[148:149]
	ds_read_b128 v[154:157], v163 offset:32768
	ds_read_b128 v[164:167], v163 offset:33792
	ds_read_b128 v[168:171], v163 offset:34816
	ds_read_b128 v[172:175], v163 offset:35840
	ds_read_b128 v[176:179], v163 offset:36864
	ds_read_b128 v[180:183], v163 offset:37888
	ds_read_b128 v[184:187], v163 offset:38912
	ds_read_b128 v[188:191], v163 offset:39936
	global_load_lds_dwordx4 v[158:159], off
	v_lshl_add_u64 v[158:159], s[0:1], 0, v[150:151]
	s_mov_b32 m0, s38
	s_nop 0
	global_load_lds_dwordx4 v[158:159], off
	s_waitcnt lgkmcnt(8)
	s_barrier
	s_waitcnt lgkmcnt(0)
	s_setprio 1
	s_waitcnt lgkmcnt(0)
	v_mfma_f32_16x16x32_bf16 v[124:127], v[128:131], v[154:157], v[124:127]
	v_mfma_f32_16x16x32_bf16 v[120:123], v[136:139], v[154:157], v[120:123]
	v_mfma_f32_16x16x32_bf16 v[108:111], v[128:131], v[168:171], v[108:111]
	v_mfma_f32_16x16x32_bf16 v[104:107], v[136:139], v[168:171], v[104:107]
	v_mfma_f32_16x16x32_bf16 v[92:95], v[128:131], v[176:179], v[92:95]
	v_mfma_f32_16x16x32_bf16 v[88:91], v[136:139], v[176:179], v[88:91]
	v_mfma_f32_16x16x32_bf16 v[76:79], v[128:131], v[184:187], v[76:79]
	v_mfma_f32_16x16x32_bf16 v[72:75], v[136:139], v[184:187], v[72:75]
	v_mfma_f32_16x16x32_bf16 v[124:127], v[132:135], v[164:167], v[124:127]
	v_mfma_f32_16x16x32_bf16 v[120:123], v[140:143], v[164:167], v[120:123]
	v_mfma_f32_16x16x32_bf16 v[108:111], v[132:135], v[172:175], v[108:111]
	v_mfma_f32_16x16x32_bf16 v[104:107], v[140:143], v[172:175], v[104:107]
	v_mfma_f32_16x16x32_bf16 v[92:95], v[132:135], v[180:183], v[92:95]
	v_mfma_f32_16x16x32_bf16 v[88:91], v[140:143], v[180:183], v[88:91]
	v_mfma_f32_16x16x32_bf16 v[76:79], v[132:135], v[188:191], v[76:79]
	v_mfma_f32_16x16x32_bf16 v[72:75], v[140:143], v[188:191], v[72:75]
	s_setprio 0
	s_barrier
	s_add_i32 s54, s89, 0x100
	v_add_u32_e32 v158, s54, v162
	s_add_i32 s0, s2, s14
	ds_read_b128 v[192:195], v158
	ds_read_b128 v[196:199], v158 offset:1024
	ds_read_b128 v[200:203], v158 offset:2048
	ds_read_b128 v[204:207], v158 offset:3072
	v_lshl_add_u64 v[158:159], s[72:73], 0, v[146:147]
	s_mov_b32 m0, s0
	s_nop 0
	global_load_lds_dwordx4 v[158:159], off
	v_lshl_add_u64 v[158:159], s[72:73], 0, v[152:153]
	s_add_i32 m0, s0, 0x2000
	s_nop 0
	global_load_lds_dwordx4 v[158:159], off
	s_barrier
	s_waitcnt lgkmcnt(0)
	s_setprio 1
	s_waitcnt lgkmcnt(0)
	v_mfma_f32_16x16x32_bf16 v[116:119], v[192:195], v[154:157], v[116:119]
	v_mfma_f32_16x16x32_bf16 v[112:115], v[200:203], v[154:157], v[112:115]
	v_mfma_f32_16x16x32_bf16 v[100:103], v[192:195], v[168:171], v[100:103]
	v_mfma_f32_16x16x32_bf16 v[96:99], v[200:203], v[168:171], v[96:99]
	v_mfma_f32_16x16x32_bf16 v[84:87], v[192:195], v[176:179], v[84:87]
	v_mfma_f32_16x16x32_bf16 v[80:83], v[200:203], v[176:179], v[80:83]
	v_mfma_f32_16x16x32_bf16 v[68:71], v[192:195], v[184:187], v[68:71]
	v_mfma_f32_16x16x32_bf16 v[64:67], v[200:203], v[184:187], v[64:67]
	v_mfma_f32_16x16x32_bf16 v[116:119], v[196:199], v[164:167], v[116:119]
	v_mfma_f32_16x16x32_bf16 v[112:115], v[204:207], v[164:167], v[112:115]
	v_mfma_f32_16x16x32_bf16 v[100:103], v[196:199], v[172:175], v[100:103]
	v_mfma_f32_16x16x32_bf16 v[96:99], v[204:207], v[172:175], v[96:99]
	v_mfma_f32_16x16x32_bf16 v[84:87], v[196:199], v[180:183], v[84:87]
	v_mfma_f32_16x16x32_bf16 v[80:83], v[204:207], v[180:183], v[80:83]
	v_mfma_f32_16x16x32_bf16 v[68:71], v[196:199], v[188:191], v[68:71]
	v_mfma_f32_16x16x32_bf16 v[64:67], v[204:207], v[188:191], v[64:67]
	s_setprio 0
	s_mov_b32 m0, s87
	v_lshl_add_u64 v[158:159], s[74:75], 0, v[148:149]
	s_barrier
	ds_read_b128 v[154:157], v163 offset:49152
	ds_read_b128 v[164:167], v163 offset:50176
	ds_read_b128 v[168:171], v163 offset:51200
	ds_read_b128 v[172:175], v163 offset:52224
	ds_read_b128 v[176:179], v163 offset:53248
	ds_read_b128 v[180:183], v163 offset:54272
	ds_read_b128 v[184:187], v163 offset:55296
	ds_read_b128 v[188:191], v163 offset:56320
	global_load_lds_dwordx4 v[158:159], off
	v_lshl_add_u64 v[158:159], s[74:75], 0, v[150:151]
	s_mov_b32 m0, s94
	s_nop 0
	global_load_lds_dwordx4 v[158:159], off
	s_barrier
; #define G_STAGE(bufoff, gbase, voff) do { _Pragma("unroll") for (int _i = 0; _i < 2; ++_i) \
;         __builtin_amdgcn_global_load_lds((const unsigned*)((const char*)(gbase) + (voff)[_i]), (LAS unsigned*)(lds + (bufoff) + ldsw + _i * 8192), 16, 0, 0); } while (0)
; #define G_MMA(ai, bj, At, Bt) do { __builtin_amdgcn_s_setprio(1); _Pragma("unroll") for (int m = 0; m < 4; ++m) _Pragma("unroll") for (int n = 0; n < 2; ++n) _Pragma("unroll") for (int k = 0; k < 2; ++k) \
;         acc[ai][bj][m][n] = __builtin_amdgcn_mfma_f32_16x16x32_bf16(Bt[n][k], At[m][k], acc[ai][bj][m][n], 0, 0, 0); __builtin_amdgcn_s_setprio(0); } while (0)
; #define G_WAIT_V(n) asm volatile("s_waitcnt vmcnt(" #n ")" ::: "memory")
; #define G_WAIT_L(n) asm volatile("s_waitcnt lgkmcnt(" #n ")" ::: "memory")
; #define G_BAR __builtin_amdgcn_s_barrier()
; #define G_SCHED __builtin_amdgcn_sched_barrier(0)
; template <class J>
; DI void gemm_phase(LAS unsigned char* lds, const J& job) {
;     ...
;       G_BAR; G_WAIT_L(0); G_MMA(1, 0, At, B0); G_BAR; G_SCHED;
;       G_STAGE(G_SB(1, 1), b3 + hstepB, voffB);
;       G_WAIT_V(6); G_BAR; G_MMA(1, 1, At, B1); G_BAR;
;     }
;   DI void epi(const Acc& acc, const Unit& u, int wr, int wc, int fr, int fq) const {
;     ...
;     for (int ai = 0; ai < 2; ++ai) {
;       f32x4 res[4][2][2];
; #pragma unroll
;       for (int m = 0; m < 4; ++m) {
;         const int row = u.pm * 256 + ai * HALF + wr * 64 + m * 16 + fr;
;         const float* src = (l == 0) ? xp + (size_t)row * DM : out + (size_t)row * DM;
; #pragma unroll
;         for (int bj = 0; bj < 2; ++bj) { const int col = u.pn * 256 + bj * HALF + wc * 32 + 8 * fq; res[m][bj][0] = *(const f32x4*)(src + col); res[m][bj][1] = *(const f32x4*)(src + col + 4); }
;       }
	s_waitcnt lgkmcnt(0)
	s_setprio 1
	s_waitcnt lgkmcnt(0)
	v_mfma_f32_16x16x32_bf16 v[60:63], v[128:131], v[154:157], v[60:63]
	v_mfma_f32_16x16x32_bf16 v[56:59], v[136:139], v[154:157], v[56:59]
	v_mfma_f32_16x16x32_bf16 v[44:47], v[128:131], v[168:171], v[44:47]
	v_mfma_f32_16x16x32_bf16 v[40:43], v[136:139], v[168:171], v[40:43]
	v_mfma_f32_16x16x32_bf16 v[28:31], v[128:131], v[176:179], v[28:31]
	v_mfma_f32_16x16x32_bf16 v[24:27], v[136:139], v[176:179], v[24:27]
	v_mfma_f32_16x16x32_bf16 v[20:23], v[128:131], v[184:187], v[20:23]
	v_mfma_f32_16x16x32_bf16 v[12:15], v[136:139], v[184:187], v[12:15]
	v_mfma_f32_16x16x32_bf16 v[60:63], v[132:135], v[164:167], v[60:63]
	v_mfma_f32_16x16x32_bf16 v[56:59], v[140:143], v[164:167], v[56:59]
	v_mfma_f32_16x16x32_bf16 v[44:47], v[132:135], v[172:175], v[44:47]
	v_mfma_f32_16x16x32_bf16 v[40:43], v[140:143], v[172:175], v[40:43]
	v_mfma_f32_16x16x32_bf16 v[28:31], v[132:135], v[180:183], v[28:31]
	v_mfma_f32_16x16x32_bf16 v[24:27], v[140:143], v[180:183], v[24:27]
	v_mfma_f32_16x16x32_bf16 v[20:23], v[132:135], v[188:191], v[20:23]
	v_mfma_f32_16x16x32_bf16 v[12:15], v[140:143], v[188:191], v[12:15]
	s_setprio 0
	s_barrier
	s_add_u32 s0, s72, 0x80000
	s_addc_u32 s1, s73, 0
	s_add_i32 s2, s54, s14
	v_lshl_add_u64 v[128:129], s[0:1], 0, v[146:147]
	s_mov_b32 m0, s2
	s_nop 0
	global_load_lds_dwordx4 v[128:129], off
	v_lshl_add_u64 v[128:129], s[0:1], 0, v[152:153]
	s_add_i32 m0, s2, 0x2000
	s_nop 0
	global_load_lds_dwordx4 v[128:129], off
	s_waitcnt vmcnt(6)
	s_barrier
	s_setprio 1
	v_mfma_f32_16x16x32_bf16 v[52:55], v[192:195], v[154:157], v[52:55]
	v_mfma_f32_16x16x32_bf16 v[48:51], v[200:203], v[154:157], v[48:51]
	v_mfma_f32_16x16x32_bf16 v[36:39], v[192:195], v[168:171], v[36:39]
	v_mfma_f32_16x16x32_bf16 v[32:35], v[200:203], v[168:171], v[32:35]
	v_mfma_f32_16x16x32_bf16 v[16:19], v[192:195], v[176:179], v[16:19]
	v_mfma_f32_16x16x32_bf16 v[8:11], v[200:203], v[176:179], v[8:11]
	v_mfma_f32_16x16x32_bf16 v[4:7], v[192:195], v[184:187], v[4:7]
	v_mfma_f32_16x16x32_bf16 v[0:3], v[200:203], v[184:187], v[0:3]
	v_mfma_f32_16x16x32_bf16 v[52:55], v[196:199], v[164:167], v[52:55]
	v_mfma_f32_16x16x32_bf16 v[48:51], v[204:207], v[164:167], v[48:51]
	v_mfma_f32_16x16x32_bf16 v[36:39], v[196:199], v[172:175], v[36:39]
	v_mfma_f32_16x16x32_bf16 v[32:35], v[204:207], v[172:175], v[32:35]
	v_mfma_f32_16x16x32_bf16 v[16:19], v[196:199], v[180:183], v[16:19]
	v_mfma_f32_16x16x32_bf16 v[8:11], v[204:207], v[180:183], v[8:11]
	v_mfma_f32_16x16x32_bf16 v[4:7], v[196:199], v[188:191], v[4:7]
	v_mfma_f32_16x16x32_bf16 v[0:3], v[204:207], v[188:191], v[0:3]
	s_setprio 0
	s_add_i32 s7, s7, 2
	s_addk_i32 s57, 0x100
	s_addk_i32 s44, 0x100
	s_cmp_gt_u32 s7, 29
	s_barrier
	s_cbranch_scc0 .LBB0_42
	s_lshl_b32 s0, s66, 8
	v_mov_b32_e32 v128, v161
	v_mov_b32_e32 v129, v160
	s_add_i32 s0, s0, s67
	s_and_b64 vcc, exec, s[18:19]
	v_add_u32_e32 v156, s0, v129
	s_lshl_b32 s0, s46, 8
	s_or_b32 s0, s0, s83
	v_lshl_add_u32 v128, v128, 3, s0
	v_ashrrev_i32_e32 v157, 31, v156
	v_ashrrev_i32_e32 v129, 31, v128
	v_lshlrev_b64 v[212:213], 13, v[156:157]
	v_lshl_add_u64 v[130:131], s[8:9], 0, v[212:213]
	v_lshlrev_b64 v[154:155], 2, v[128:129]
	v_lshl_add_u64 v[128:129], v[130:131], 0, v[154:155]
	global_load_dwordx4 v[164:167], v[128:129], off offset:16
	global_load_dwordx4 v[168:171], v[128:129], off
	global_load_dwordx4 v[172:175], v[128:129], off offset:528
	global_load_dwordx4 v[176:179], v[128:129], off offset:512
	v_add_u32_e32 v128, 16, v156
	v_ashrrev_i32_e32 v129, 31, v128
	v_lshlrev_b64 v[214:215], 13, v[128:129]
	v_lshl_add_u64 v[128:129], s[8:9], 0, v[214:215]
	v_lshl_add_u64 v[128:129], v[128:129], 0, v[154:155]
	global_load_dwordx4 v[180:183], v[128:129], off offset:16
	global_load_dwordx4 v[184:187], v[128:129], off
	global_load_dwordx4 v[188:191], v[128:129], off offset:528
	global_load_dwordx4 v[192:195], v[128:129], off offset:512
	v_add_u32_e32 v128, 32, v156
	v_ashrrev_i32_e32 v129, 31, v128
	v_lshlrev_b64 v[216:217], 13, v[128:129]
	v_lshl_add_u64 v[128:129], s[8:9], 0, v[216:217]
	v_lshl_add_u64 v[128:129], v[128:129], 0, v[154:155]
	global_load_dwordx4 v[196:199], v[128:129], off offset:16
	global_load_dwordx4 v[200:203], v[128:129], off
	global_load_dwordx4 v[204:207], v[128:129], off offset:528
	global_load_dwordx4 v[208:211], v[128:129], off offset:512
	v_add_u32_e32 v128, 48, v156
	v_ashrrev_i32_e32 v129, 31, v128
	v_lshlrev_b64 v[158:159], 13, v[128:129]
	v_lshl_add_u64 v[128:129], s[8:9], 0, v[158:159]
	v_lshl_add_u64 v[136:137], v[128:129], 0, v[154:155]
	global_load_dwordx4 v[132:135], v[136:137], off offset:16
	global_load_dwordx4 v[140:143], v[136:137], off
	global_load_dwordx4 v[128:131], v[136:137], off offset:528
	s_nop 0
	global_load_dwordx4 v[136:139], v[136:137], off offset:512
	v_lshl_add_u64 v[212:213], s[16:17], 0, v[212:213]
	s_mov_b32 s46, s22
	s_mov_b32 s66, s20
	s_mov_b64 s[68:69], s[64:65]
	s_mov_b64 s[70:71], s[62:63]
	s_movk_i32 s54, 0x4000
	s_movk_i32 s55, 0x6000
	v_readlane_b32 s0, v255, 23
	s_cmpk_gt_u32 s0, 0xff
	s_cbranch_scc1 .Lds_out_x
	s_barrier
;   DI void epi(const Acc& acc, const Unit& u, int wr, int wc, int fr, int fq) const {
;     ...
;     for (int ai = 0; ai < 2; ++ai) {
;       f32x4 res[4][2][2];
; #pragma unroll
;       for (int m = 0; m < 4; ++m) {
;         const int row = u.pm * 256 + ai * HALF + wr * 64 + m * 16 + fr;
;         const float* src = (l == 0) ? xp + (size_t)row * DM : out + (size_t)row * DM;
; #pragma unroll
;         for (int bj = 0; bj < 2; ++bj) { const int col = u.pn * 256 + bj * HALF + wc * 32 + 8 * fq; res[m][bj][0] = *(const f32x4*)(src + col); res[m][bj][1] = *(const f32x4*)(src + col + 4); }
;       }
;       asm volatile("" ::: "memory");
; #pragma unroll
;       for (int m = 0; m < 4; ++m) {
;         const int row = u.pm * 256 + ai * HALF + wr * 64 + m * 16 + fr;
;         float* dst = out + (size_t)row * DM;
; #pragma unroll
;         for (int bj = 0; bj < 2; ++bj) { const int col = u.pn * 256 + bj * HALF + wc * 32 + 8 * fq;
;           *(f32x4*)(dst + col) = acc[ai][bj][m][0] + res[m][bj][0]; *(f32x4*)(dst + col + 4) = acc[ai][bj][m][1] + res[m][bj][1]; }
;       }
.Lds_out_x:
	s_waitcnt vmcnt(0)
	v_pk_add_f32 v[122:123], v[122:123], v[166:167]
	v_pk_add_f32 v[124:125], v[124:125], v[168:169]
	v_lshl_add_u64 v[168:169], v[212:213], 0, v[154:155]
	v_pk_add_f32 v[114:115], v[114:115], v[174:175]
	v_pk_add_f32 v[112:113], v[112:113], v[172:173]
	global_store_dwordx4 v[168:169], v[112:115], off offset:528
	v_pk_add_f32 v[126:127], v[126:127], v[170:171]
	v_pk_add_f32 v[120:121], v[120:121], v[164:165]
	v_lshl_add_u64 v[112:113], s[16:17], 0, v[214:215]
	v_lshl_add_u64 v[112:113], v[112:113], 0, v[154:155]
	v_pk_add_f32 v[98:99], v[98:99], v[190:191]
	v_pk_add_f32 v[96:97], v[96:97], v[188:189]
	global_store_dwordx4 v[112:113], v[96:99], off offset:528
	v_pk_add_f32 v[118:119], v[118:119], v[178:179]
	v_pk_add_f32 v[82:83], v[82:83], v[206:207]
	v_lshl_add_u64 v[96:97], s[16:17], 0, v[216:217]
	v_lshl_add_u64 v[96:97], v[96:97], 0, v[154:155]
	v_pk_add_f32 v[80:81], v[80:81], v[204:205]
	global_store_dwordx4 v[96:97], v[80:83], off offset:528
	v_pk_add_f32 v[116:117], v[116:117], v[176:177]
	v_pk_add_f32 v[66:67], v[66:67], v[130:131]
	v_lshl_add_u64 v[80:81], s[16:17], 0, v[158:159]
	v_lshl_add_u64 v[80:81], v[80:81], 0, v[154:155]
	v_pk_add_f32 v[64:65], v[64:65], v[128:129]
	global_store_dwordx4 v[80:81], v[64:67], off offset:528
	v_pk_add_f32 v[110:111], v[110:111], v[186:187]
	v_pk_add_f32 v[108:109], v[108:109], v[184:185]
	v_add_u32_e32 v64, 0x80, v156
	v_ashrrev_i32_e32 v65, 31, v64
	v_lshlrev_b64 v[130:131], 13, v[64:65]
	v_pk_add_f32 v[106:107], v[106:107], v[182:183]
	v_pk_add_f32 v[104:105], v[104:105], v[180:181]
	v_pk_add_f32 v[102:103], v[102:103], v[194:195]
	v_pk_add_f32 v[100:101], v[100:101], v[192:193]
	v_pk_add_f32 v[94:95], v[94:95], v[202:203]
	v_pk_add_f32 v[92:93], v[92:93], v[200:201]
	v_pk_add_f32 v[90:91], v[90:91], v[198:199]
	v_pk_add_f32 v[88:89], v[88:89], v[196:197]
	v_pk_add_f32 v[86:87], v[86:87], v[210:211]
	v_pk_add_f32 v[84:85], v[84:85], v[208:209]
	v_pk_add_f32 v[78:79], v[78:79], v[142:143]
	v_pk_add_f32 v[76:77], v[76:77], v[140:141]
	v_pk_add_f32 v[74:75], v[74:75], v[134:135]
	v_pk_add_f32 v[72:73], v[72:73], v[132:133]
	v_pk_add_f32 v[70:71], v[70:71], v[138:139]
	v_pk_add_f32 v[68:69], v[68:69], v[136:137]
	v_lshl_add_u64 v[64:65], s[8:9], 0, v[130:131]
	global_store_dwordx4 v[168:169], v[124:127], off
	global_store_dwordx4 v[168:169], v[120:123], off offset:16
	global_store_dwordx4 v[168:169], v[116:119], off offset:512
	global_store_dwordx4 v[112:113], v[108:111], off
	global_store_dwordx4 v[112:113], v[104:107], off offset:16
	global_store_dwordx4 v[112:113], v[100:103], off offset:512
	global_store_dwordx4 v[96:97], v[92:95], off
	global_store_dwordx4 v[96:97], v[88:91], off offset:16
	global_store_dwordx4 v[96:97], v[84:87], off offset:512
	global_store_dwordx4 v[80:81], v[76:79], off
	global_store_dwordx4 v[80:81], v[72:75], off offset:16
	global_store_dwordx4 v[80:81], v[68:71], off offset:512
	v_lshl_add_u64 v[64:65], v[64:65], 0, v[154:155]
	global_load_dwordx4 v[94:97], v[64:65], off offset:16
	global_load_dwordx4 v[98:101], v[64:65], off
	global_load_dwordx4 v[102:105], v[64:65], off offset:528
	global_load_dwordx4 v[106:109], v[64:65], off offset:512
	v_add_u32_e32 v64, 0x90, v156
	v_ashrrev_i32_e32 v65, 31, v64
	v_lshlrev_b64 v[132:133], 13, v[64:65]
	v_lshl_add_u64 v[64:65], s[8:9], 0, v[132:133]
	v_lshl_add_u64 v[64:65], v[64:65], 0, v[154:155]
	global_load_dwordx4 v[110:113], v[64:65], off offset:16
	global_load_dwordx4 v[114:117], v[64:65], off
	global_load_dwordx4 v[118:121], v[64:65], off offset:528
	global_load_dwordx4 v[122:125], v[64:65], off offset:512
	v_add_u32_e32 v64, 0xa0, v156
	v_ashrrev_i32_e32 v65, 31, v64
	v_lshlrev_b64 v[134:135], 13, v[64:65]
	v_lshl_add_u64 v[64:65], s[8:9], 0, v[134:135]
	v_lshl_add_u64 v[64:65], v[64:65], 0, v[154:155]
	global_load_dwordx4 v[84:87], v[64:65], off offset:16
	global_load_dwordx4 v[126:129], v[64:65], off
	global_load_dwordx4 v[72:75], v[64:65], off offset:528
	global_load_dwordx4 v[88:91], v[64:65], off offset:512
	v_add_u32_e32 v64, 0xb0, v156
	v_ashrrev_i32_e32 v65, 31, v64
	v_lshlrev_b64 v[92:93], 13, v[64:65]
	v_lshl_add_u64 v[64:65], s[8:9], 0, v[92:93]
	v_lshl_add_u64 v[76:77], v[64:65], 0, v[154:155]
	global_load_dwordx4 v[68:71], v[76:77], off offset:16
	global_load_dwordx4 v[80:83], v[76:77], off
	global_load_dwordx4 v[64:67], v[76:77], off offset:528
	s_nop 0
	global_load_dwordx4 v[76:79], v[76:77], off offset:512
	v_lshl_add_u64 v[130:131], s[16:17], 0, v[130:131]
	s_waitcnt vmcnt(0)
; #define G_WAIT_V(n) asm volatile("s_waitcnt vmcnt(" #n ")" ::: "memory")
; #define G_BAR __builtin_amdgcn_s_barrier()
; template <class J>
; DI void gemm_phase(LAS unsigned char* lds, const J& job) {
;     ...
;     if (!has_next) break;
; #pragma unroll
;     for (int a = 0; a < 2; ++a)
; #pragma unroll
;       for (int b = 0; b < 2; ++b)
; #pragma unroll
;         for (int m = 0; m < 4; ++m)
; #pragma unroll
;           for (int n = 0; n < 2; ++n) acc[a][b][m][n] = (f32x4){0.f, 0.f, 0.f, 0.f};
;     cur = nxt; cA = nA; cB = nB; ++ui;
;   }
;   G_WAIT_V(0);
;   if (wr == 0) G_BAR;
;   G_BAR;
;   DI void epi(const Acc& acc, const Unit& u, int wr, int wc, int fr, int fq) const {
;     ...
; #pragma unroll
;       for (int m = 0; m < 4; ++m) {
;         const int row = u.pm * 256 + ai * HALF + wr * 64 + m * 16 + fr;
;         float* dst = out + (size_t)row * DM;
; #pragma unroll
;         for (int bj = 0; bj < 2; ++bj) { const int col = u.pn * 256 + bj * HALF + wc * 32 + 8 * fq;
;           *(f32x4*)(dst + col) = acc[ai][bj][m][0] + res[m][bj][0]; *(f32x4*)(dst + col + 4) = acc[ai][bj][m][1] + res[m][bj][1]; }
;       }
	v_pk_add_f32 v[58:59], v[58:59], v[96:97]
	v_pk_add_f32 v[60:61], v[60:61], v[98:99]
	v_lshl_add_u64 v[98:99], v[130:131], 0, v[154:155]
	v_pk_add_f32 v[50:51], v[50:51], v[104:105]
	v_pk_add_f32 v[48:49], v[48:49], v[102:103]
	global_store_dwordx4 v[98:99], v[48:51], off offset:528
	v_pk_add_f32 v[62:63], v[62:63], v[100:101]
	v_pk_add_f32 v[56:57], v[56:57], v[94:95]
	v_lshl_add_u64 v[48:49], s[16:17], 0, v[132:133]
	v_lshl_add_u64 v[48:49], v[48:49], 0, v[154:155]
	v_pk_add_f32 v[34:35], v[34:35], v[120:121]
	v_pk_add_f32 v[32:33], v[32:33], v[118:119]
	global_store_dwordx4 v[48:49], v[32:35], off offset:528
	v_pk_add_f32 v[54:55], v[54:55], v[108:109]
	v_pk_add_f32 v[10:11], v[10:11], v[74:75]
	v_lshl_add_u64 v[32:33], s[16:17], 0, v[134:135]
	v_lshl_add_u64 v[32:33], v[32:33], 0, v[154:155]
	v_pk_add_f32 v[18:19], v[18:19], v[90:91]
	v_pk_add_f32 v[16:17], v[16:17], v[88:89]
	global_store_dwordx4 v[32:33], v[16:19], off offset:512
	v_pk_add_f32 v[8:9], v[8:9], v[72:73]
	global_store_dwordx4 v[32:33], v[8:11], off offset:528
	v_lshl_add_u64 v[16:17], s[16:17], 0, v[92:93]
	v_lshl_add_u64 v[16:17], v[16:17], 0, v[154:155]
	v_pk_add_f32 v[10:11], v[22:23], v[82:83]
	v_pk_add_f32 v[8:9], v[20:21], v[80:81]
	v_pk_add_f32 v[52:53], v[52:53], v[106:107]
	v_pk_add_f32 v[46:47], v[46:47], v[116:117]
	v_pk_add_f32 v[44:45], v[44:45], v[114:115]
	v_pk_add_f32 v[42:43], v[42:43], v[112:113]
	v_pk_add_f32 v[40:41], v[40:41], v[110:111]
	v_pk_add_f32 v[38:39], v[38:39], v[124:125]
	v_pk_add_f32 v[36:37], v[36:37], v[122:123]
	v_pk_add_f32 v[30:31], v[30:31], v[128:129]
	v_pk_add_f32 v[28:29], v[28:29], v[126:127]
	v_pk_add_f32 v[26:27], v[26:27], v[86:87]
	v_pk_add_f32 v[24:25], v[24:25], v[84:85]
	global_store_dwordx4 v[16:17], v[8:11], off
	v_pk_add_f32 v[6:7], v[6:7], v[78:79]
	v_pk_add_f32 v[4:5], v[4:5], v[76:77]
	v_pk_add_f32 v[10:11], v[14:15], v[70:71]
	v_pk_add_f32 v[8:9], v[12:13], v[68:69]
	v_pk_add_f32 v[2:3], v[2:3], v[66:67]
	v_pk_add_f32 v[0:1], v[0:1], v[64:65]
	global_store_dwordx4 v[98:99], v[60:63], off
	global_store_dwordx4 v[98:99], v[56:59], off offset:16
	global_store_dwordx4 v[98:99], v[52:55], off offset:512
	global_store_dwordx4 v[48:49], v[44:47], off
	global_store_dwordx4 v[48:49], v[40:43], off offset:16
	global_store_dwordx4 v[48:49], v[36:39], off offset:512
	global_store_dwordx4 v[32:33], v[28:31], off
	global_store_dwordx4 v[32:33], v[24:27], off offset:16
	global_store_dwordx4 v[16:17], v[8:11], off offset:16
	global_store_dwordx4 v[16:17], v[4:7], off offset:512
	global_store_dwordx4 v[16:17], v[0:3], off offset:528
	s_cbranch_vccnz .Lds_out_done
	v_readlane_b32 s0, v255, 23
	s_cmpk_gt_u32 s0, 0xff
	s_cbranch_scc0 .LBB0_35
	s_barrier
	s_branch .LBB0_35
.Lds_out_done:
	s_waitcnt vmcnt(0)
	v_readlane_b32 s0, v255, 23
	s_cmpk_gt_u32 s0, 0xff
	s_cbranch_scc1 .LBB0_46

; #define G_STAGE(bufoff, gbase, voff) do { _Pragma("unroll") for (int _i = 0; _i < 2; ++_i) \
;         __builtin_amdgcn_global_load_lds((const unsigned*)((const char*)(gbase) + (voff)[_i]), (LAS unsigned*)(lds + (bufoff) + ldsw + _i * 8192), 16, 0, 0); } while (0)
; #define G_LDA(dst, b, h) do { _Pragma("unroll") for (int m = 0; m < 4; ++m) _Pragma("unroll") for (int k = 0; k < 2; ++k) dst[m][k] = *(const LAS bf16x8*)(lds + G_SA(b, h) + aoff + m * 2048 + k * 1024); } while (0)
; #define G_LDB(dst, b, h) do { _Pragma("unroll") for (int n = 0; n < 2; ++n) _Pragma("unroll") for (int k = 0; k < 2; ++k) dst[n][k] = *(const LAS bf16x8*)(lds + G_SB(b, h) + boff + n * 2048 + k * 1024); } while (0)
; #define G_MMA(ai, bj, At, Bt) do { __builtin_amdgcn_s_setprio(1); _Pragma("unroll") for (int m = 0; m < 4; ++m) _Pragma("unroll") for (int n = 0; n < 2; ++n) _Pragma("unroll") for (int k = 0; k < 2; ++k) \
;         acc[ai][bj][m][n] = __builtin_amdgcn_mfma_f32_16x16x32_bf16(Bt[n][k], At[m][k], acc[ai][bj][m][n], 0, 0, 0); __builtin_amdgcn_s_setprio(0); } while (0)
; #define G_WAIT_L(n) asm volatile("s_waitcnt lgkmcnt(" #n ")" ::: "memory")
; #define G_BAR __builtin_amdgcn_s_barrier()
; #define G_SCHED __builtin_amdgcn_sched_barrier(0)
; template <class J>
; DI void gemm_phase(LAS unsigned char* lds, const J& job) {
;     ...
;       const bool last = (t == nt - 2);
;       const char* a1 = cA + G_KT(t + 1);
;       const char* a2 = last ? nA + G_KT(0) : cA + G_KT(t + 2); const char* b2 = last ? nB + G_KT(0) : cB + G_KT(t + 2);
;       const char* a3 = last ? nA + G_KT(1) : cA + G_KT(t + 3); const char* b3 = last ? nB + G_KT(1) : cB + G_KT(t + 3);
;       G_LDB(B0, 0, 0); G_SCHED; G_LDA(At, 0, 0); G_STAGE(G_SA(1, 1), a1 + hstepA, voffA);
;       G_WAIT_L(8); G_BAR; G_WAIT_L(0); G_MMA(0, 0, At, B0); G_BAR; G_SCHED;
;       G_LDB(B1, 0, 1); G_STAGE(G_SB(0, 0), b2, voffB);
;       G_BAR; G_WAIT_L(0); G_MMA(0, 1, At, B1); G_BAR;
;       G_LDA(At, 0, 1); G_STAGE(G_SA(0, 0), a2, voffA);
;       G_BAR; G_WAIT_L(0); G_MMA(1, 0, At, B0); G_BAR; G_SCHED;
.LBB0_74:
	s_add_i32 s1, s56, 0xffffff80
	s_and_b32 s0, s7, 0xf80
	s_and_b32 s1, s1, 0xf00
	s_add_u32 s57, s68, s1
	s_addc_u32 s70, s69, 0
	s_add_u32 s1, s66, s1
	s_addc_u32 s71, s67, 0
	s_and_b32 s72, s56, 0xf80
	s_add_u32 s80, s68, s72
	s_addc_u32 s73, s69, 0
	s_add_u32 s38, s66, s72
	s_addc_u32 s2, s67, 0
	s_cmp_eq_u32 s6, 28
	s_cselect_b32 s75, s46, s70
	s_cselect_b32 s74, s45, s57
	s_cselect_b32 s77, vcc_lo, s71
	s_cselect_b32 s76, s47, s1
	s_cselect_b32 s73, s97, s73
	s_cselect_b32 s72, s33, s80
	s_cselect_b32 s71, s5, s2
	s_cselect_b32 s70, vcc_hi, s38
	s_add_i32 s2, s84, 0x100
	v_add_u32_e32 v100, s2, v248
	ds_read_b128 v[84:87], v100
	ds_read_b128 v[88:91], v100 offset:1024
	ds_read_b128 v[96:99], v100 offset:2048
	ds_read_b128 v[100:103], v100 offset:3072
	s_add_u32 s0, s19, s0
	s_addc_u32 s1, s21, 0
	v_lshl_add_u64 v[186:187], s[0:1], 0, v[148:149]
	s_add_i32 m0, s14, 0xc000
	ds_read_b128 v[154:157], v249
	ds_read_b128 v[158:161], v249 offset:1024
	ds_read_b128 v[162:165], v249 offset:2048
	ds_read_b128 v[166:169], v249 offset:3072
	ds_read_b128 v[170:173], v249 offset:4096
	ds_read_b128 v[174:177], v249 offset:5120
	ds_read_b128 v[178:181], v249 offset:6144
	ds_read_b128 v[182:185], v249 offset:7168
	global_load_lds_dwordx4 v[186:187], off
	v_lshl_add_u64 v[186:187], s[0:1], 0, v[150:151]
	s_add_i32 m0, s14, 0xe000
	s_nop 0
	global_load_lds_dwordx4 v[186:187], off
	s_waitcnt lgkmcnt(8)
	s_barrier
	s_waitcnt lgkmcnt(0)
	s_setprio 1
	s_waitcnt lgkmcnt(0)
	v_mfma_f32_16x16x32_bf16 v[140:143], v[84:87], v[154:157], v[140:143]
	v_mfma_f32_16x16x32_bf16 v[136:139], v[96:99], v[154:157], v[136:139]
	v_mfma_f32_16x16x32_bf16 v[124:127], v[84:87], v[162:165], v[124:127]
	v_mfma_f32_16x16x32_bf16 v[120:123], v[96:99], v[162:165], v[120:123]
	v_mfma_f32_16x16x32_bf16 v[108:111], v[84:87], v[170:173], v[108:111]
	v_mfma_f32_16x16x32_bf16 v[104:107], v[96:99], v[170:173], v[104:107]
	v_mfma_f32_16x16x32_bf16 v[76:79], v[84:87], v[178:181], v[76:79]
	v_mfma_f32_16x16x32_bf16 v[72:75], v[96:99], v[178:181], v[72:75]
	v_mfma_f32_16x16x32_bf16 v[140:143], v[88:91], v[158:161], v[140:143]
	v_mfma_f32_16x16x32_bf16 v[136:139], v[100:103], v[158:161], v[136:139]
	v_mfma_f32_16x16x32_bf16 v[124:127], v[88:91], v[166:169], v[124:127]
	v_mfma_f32_16x16x32_bf16 v[120:123], v[100:103], v[166:169], v[120:123]
	v_mfma_f32_16x16x32_bf16 v[108:111], v[88:91], v[174:177], v[108:111]
	v_mfma_f32_16x16x32_bf16 v[104:107], v[100:103], v[174:177], v[104:107]
	v_mfma_f32_16x16x32_bf16 v[76:79], v[88:91], v[182:185], v[76:79]
	v_mfma_f32_16x16x32_bf16 v[72:75], v[100:103], v[182:185], v[72:75]
	s_setprio 0
	s_barrier
	s_add_i32 s38, s85, 0x100
	s_add_i32 s0, s2, s78
	v_add_u32_e32 v198, s38, v248
	v_lshl_add_u64 v[202:203], s[76:77], 0, v[146:147]
	s_mov_b32 m0, s0
	ds_read_b128 v[186:189], v198
	ds_read_b128 v[190:193], v198 offset:1024
	ds_read_b128 v[194:197], v198 offset:2048
	ds_read_b128 v[198:201], v198 offset:3072
	global_load_lds_dwordx4 v[202:203], off
	v_lshl_add_u64 v[202:203], s[76:77], 0, v[152:153]
	s_add_i32 m0, s0, 0x2000
	s_nop 0
	global_load_lds_dwordx4 v[202:203], off
	s_barrier
	s_waitcnt lgkmcnt(0)
	s_setprio 1
	s_waitcnt lgkmcnt(0)
	v_mfma_f32_16x16x32_bf16 v[132:135], v[186:189], v[154:157], v[132:135]
	v_mfma_f32_16x16x32_bf16 v[128:131], v[194:197], v[154:157], v[128:131]
	v_mfma_f32_16x16x32_bf16 v[116:119], v[186:189], v[162:165], v[116:119]
	v_mfma_f32_16x16x32_bf16 v[112:115], v[194:197], v[162:165], v[112:115]
	v_mfma_f32_16x16x32_bf16 v[92:95], v[186:189], v[170:173], v[92:95]
	v_mfma_f32_16x16x32_bf16 v[80:83], v[194:197], v[170:173], v[80:83]
	v_mfma_f32_16x16x32_bf16 v[68:71], v[186:189], v[178:181], v[68:71]
	v_mfma_f32_16x16x32_bf16 v[64:67], v[194:197], v[178:181], v[64:67]
	v_mfma_f32_16x16x32_bf16 v[132:135], v[190:193], v[158:161], v[132:135]
	v_mfma_f32_16x16x32_bf16 v[128:131], v[198:201], v[158:161], v[128:131]
	v_mfma_f32_16x16x32_bf16 v[116:119], v[190:193], v[166:169], v[116:119]
	v_mfma_f32_16x16x32_bf16 v[112:115], v[198:201], v[166:169], v[112:115]
	v_mfma_f32_16x16x32_bf16 v[92:95], v[190:193], v[174:177], v[92:95]
	v_mfma_f32_16x16x32_bf16 v[80:83], v[198:201], v[174:177], v[80:83]
	v_mfma_f32_16x16x32_bf16 v[68:71], v[190:193], v[182:185], v[68:71]
	v_mfma_f32_16x16x32_bf16 v[64:67], v[198:201], v[182:185], v[64:67]
	s_setprio 0
	s_mov_b32 m0, s14
	v_lshl_add_u64 v[202:203], s[74:75], 0, v[148:149]
	s_barrier
	ds_read_b128 v[154:157], v249 offset:16384
	ds_read_b128 v[158:161], v249 offset:17408
	ds_read_b128 v[162:165], v249 offset:18432
	ds_read_b128 v[166:169], v249 offset:19456
	ds_read_b128 v[170:173], v249 offset:20480
	ds_read_b128 v[174:177], v249 offset:21504
	ds_read_b128 v[178:181], v249 offset:22528
	ds_read_b128 v[182:185], v249 offset:23552
	global_load_lds_dwordx4 v[202:203], off
	v_lshl_add_u64 v[202:203], s[74:75], 0, v[150:151]
	s_mov_b32 m0, s15
	s_nop 0
	global_load_lds_dwordx4 v[202:203], off
	s_barrier
	s_waitcnt lgkmcnt(0)
	s_setprio 1
	s_waitcnt lgkmcnt(0)
	v_mfma_f32_16x16x32_bf16 v[60:63], v[84:87], v[154:157], v[60:63]
	v_mfma_f32_16x16x32_bf16 v[56:59], v[96:99], v[154:157], v[56:59]
	v_mfma_f32_16x16x32_bf16 v[44:47], v[84:87], v[162:165], v[44:47]
	v_mfma_f32_16x16x32_bf16 v[40:43], v[96:99], v[162:165], v[40:43]
	v_mfma_f32_16x16x32_bf16 v[28:31], v[84:87], v[170:173], v[28:31]
	v_mfma_f32_16x16x32_bf16 v[24:27], v[96:99], v[170:173], v[24:27]
	v_mfma_f32_16x16x32_bf16 v[12:15], v[84:87], v[178:181], v[12:15]
	v_mfma_f32_16x16x32_bf16 v[8:11], v[96:99], v[178:181], v[8:11]
	v_mfma_f32_16x16x32_bf16 v[60:63], v[88:91], v[158:161], v[60:63]
	v_mfma_f32_16x16x32_bf16 v[56:59], v[100:103], v[158:161], v[56:59]
	v_mfma_f32_16x16x32_bf16 v[44:47], v[88:91], v[166:169], v[44:47]
	v_mfma_f32_16x16x32_bf16 v[40:43], v[100:103], v[166:169], v[40:43]
	v_mfma_f32_16x16x32_bf16 v[28:31], v[88:91], v[174:177], v[28:31]
	v_mfma_f32_16x16x32_bf16 v[24:27], v[100:103], v[174:177], v[24:27]
	v_mfma_f32_16x16x32_bf16 v[12:15], v[88:91], v[182:185], v[12:15]
	v_mfma_f32_16x16x32_bf16 v[8:11], v[100:103], v[182:185], v[8:11]
	s_setprio 0
	s_barrier
; #define G_STAGE(bufoff, gbase, voff) do { _Pragma("unroll") for (int _i = 0; _i < 2; ++_i) \
;         __builtin_amdgcn_global_load_lds((const unsigned*)((const char*)(gbase) + (voff)[_i]), (LAS unsigned*)(lds + (bufoff) + ldsw + _i * 8192), 16, 0, 0); } while (0)
; #define G_LDA(dst, b, h) do { _Pragma("unroll") for (int m = 0; m < 4; ++m) _Pragma("unroll") for (int k = 0; k < 2; ++k) dst[m][k] = *(const LAS bf16x8*)(lds + G_SA(b, h) + aoff + m * 2048 + k * 1024); } while (0)
; #define G_LDB(dst, b, h) do { _Pragma("unroll") for (int n = 0; n < 2; ++n) _Pragma("unroll") for (int k = 0; k < 2; ++k) dst[n][k] = *(const LAS bf16x8*)(lds + G_SB(b, h) + boff + n * 2048 + k * 1024); } while (0)
; #define G_MMA(ai, bj, At, Bt) do { __builtin_amdgcn_s_setprio(1); _Pragma("unroll") for (int m = 0; m < 4; ++m) _Pragma("unroll") for (int n = 0; n < 2; ++n) _Pragma("unroll") for (int k = 0; k < 2; ++k) \
;         acc[ai][bj][m][n] = __builtin_amdgcn_mfma_f32_16x16x32_bf16(Bt[n][k], At[m][k], acc[ai][bj][m][n], 0, 0, 0); __builtin_amdgcn_s_setprio(0); } while (0)
; #define G_WAIT_V(n) asm volatile("s_waitcnt vmcnt(" #n ")" ::: "memory")
; #define G_WAIT_L(n) asm volatile("s_waitcnt lgkmcnt(" #n ")" ::: "memory")
; #define G_BAR __builtin_amdgcn_s_barrier()
; #define G_SCHED __builtin_amdgcn_sched_barrier(0)
; template <class J>
; DI void gemm_phase(LAS unsigned char* lds, const J& job) {
;     ...
;       G_STAGE(G_SB(0, 1), b2 + hstepB, voffB);
;       G_WAIT_V(6); G_BAR; G_MMA(1, 1, At, B1); G_BAR;
;       G_LDB(B0, 1, 0); G_SCHED; G_LDA(At, 1, 0); G_STAGE(G_SA(0, 1), a2 + hstepA, voffA);
;       G_WAIT_L(8); G_BAR; G_WAIT_L(0); G_MMA(0, 0, At, B0); G_BAR; G_SCHED;
;       G_LDB(B1, 1, 1); G_STAGE(G_SB(1, 0), b3, voffB);
;       G_BAR; G_WAIT_L(0); G_MMA(0, 1, At, B1); G_BAR;
;       G_LDA(At, 1, 1); G_STAGE(G_SA(1, 0), a3, voffA);
	s_add_u32 s0, s76, 0x1000000
	s_addc_u32 s1, s77, 0
	s_add_i32 s2, s38, s78
	v_lshl_add_u64 v[84:85], s[0:1], 0, v[146:147]
	s_mov_b32 m0, s2
	s_nop 0
	global_load_lds_dwordx4 v[84:85], off
	v_lshl_add_u64 v[84:85], s[0:1], 0, v[152:153]
	s_add_i32 m0, s2, 0x2000
	s_nop 0
	global_load_lds_dwordx4 v[84:85], off
	s_waitcnt vmcnt(6)
	s_barrier
	s_setprio 1
	v_mfma_f32_16x16x32_bf16 v[52:55], v[186:189], v[154:157], v[52:55]
	v_mfma_f32_16x16x32_bf16 v[48:51], v[194:197], v[154:157], v[48:51]
	v_mfma_f32_16x16x32_bf16 v[36:39], v[186:189], v[162:165], v[36:39]
	v_mfma_f32_16x16x32_bf16 v[32:35], v[194:197], v[162:165], v[32:35]
	v_mfma_f32_16x16x32_bf16 v[20:23], v[186:189], v[170:173], v[20:23]
	v_mfma_f32_16x16x32_bf16 v[16:19], v[194:197], v[170:173], v[16:19]
	v_mfma_f32_16x16x32_bf16 v[4:7], v[186:189], v[178:181], v[4:7]
	v_mfma_f32_16x16x32_bf16 v[0:3], v[194:197], v[178:181], v[0:3]
	v_mfma_f32_16x16x32_bf16 v[52:55], v[190:193], v[158:161], v[52:55]
	v_mfma_f32_16x16x32_bf16 v[48:51], v[198:201], v[158:161], v[48:51]
	v_mfma_f32_16x16x32_bf16 v[36:39], v[190:193], v[166:169], v[36:39]
	v_mfma_f32_16x16x32_bf16 v[32:35], v[198:201], v[166:169], v[32:35]
	v_mfma_f32_16x16x32_bf16 v[20:23], v[190:193], v[174:177], v[20:23]
	v_mfma_f32_16x16x32_bf16 v[16:19], v[198:201], v[174:177], v[16:19]
	v_mfma_f32_16x16x32_bf16 v[4:7], v[190:193], v[182:185], v[4:7]
	v_mfma_f32_16x16x32_bf16 v[0:3], v[198:201], v[182:185], v[0:3]
	s_setprio 0
	s_add_i32 s2, s88, 0x100
	v_add_u32_e32 v100, s2, v248
	s_barrier
	ds_read_b128 v[84:87], v100
	ds_read_b128 v[88:91], v100 offset:1024
	ds_read_b128 v[96:99], v100 offset:2048
	ds_read_b128 v[100:103], v100 offset:3072
	s_add_u32 s0, s74, 0x80000
	s_addc_u32 s1, s75, 0
	s_mov_b32 m0, s83
	v_lshl_add_u64 v[186:187], s[0:1], 0, v[148:149]
	ds_read_b128 v[154:157], v249 offset:32768
	ds_read_b128 v[158:161], v249 offset:33792
	ds_read_b128 v[162:165], v249 offset:34816
	ds_read_b128 v[166:169], v249 offset:35840
	ds_read_b128 v[170:173], v249 offset:36864
	ds_read_b128 v[174:177], v249 offset:37888
	ds_read_b128 v[178:181], v249 offset:38912
	ds_read_b128 v[182:185], v249 offset:39936
	global_load_lds_dwordx4 v[186:187], off
	v_lshl_add_u64 v[186:187], s[0:1], 0, v[150:151]
	s_mov_b32 m0, s36
	s_nop 0
	global_load_lds_dwordx4 v[186:187], off
	s_waitcnt lgkmcnt(8)
	s_barrier
	s_waitcnt lgkmcnt(0)
	s_setprio 1
	s_waitcnt lgkmcnt(0)
	v_mfma_f32_16x16x32_bf16 v[140:143], v[84:87], v[154:157], v[140:143]
	v_mfma_f32_16x16x32_bf16 v[136:139], v[96:99], v[154:157], v[136:139]
	v_mfma_f32_16x16x32_bf16 v[124:127], v[84:87], v[162:165], v[124:127]
	v_mfma_f32_16x16x32_bf16 v[120:123], v[96:99], v[162:165], v[120:123]
	v_mfma_f32_16x16x32_bf16 v[108:111], v[84:87], v[170:173], v[108:111]
	v_mfma_f32_16x16x32_bf16 v[104:107], v[96:99], v[170:173], v[104:107]
	v_mfma_f32_16x16x32_bf16 v[76:79], v[84:87], v[178:181], v[76:79]
	v_mfma_f32_16x16x32_bf16 v[72:75], v[96:99], v[178:181], v[72:75]
	v_mfma_f32_16x16x32_bf16 v[140:143], v[88:91], v[158:161], v[140:143]
	v_mfma_f32_16x16x32_bf16 v[136:139], v[100:103], v[158:161], v[136:139]
	v_mfma_f32_16x16x32_bf16 v[124:127], v[88:91], v[166:169], v[124:127]
	v_mfma_f32_16x16x32_bf16 v[120:123], v[100:103], v[166:169], v[120:123]
	v_mfma_f32_16x16x32_bf16 v[108:111], v[88:91], v[174:177], v[108:111]
	v_mfma_f32_16x16x32_bf16 v[104:107], v[100:103], v[174:177], v[104:107]
	v_mfma_f32_16x16x32_bf16 v[76:79], v[88:91], v[182:185], v[76:79]
	v_mfma_f32_16x16x32_bf16 v[72:75], v[100:103], v[182:185], v[72:75]
	s_setprio 0
	s_barrier
	s_add_i32 s38, s89, 0x100
	s_add_i32 s0, s2, s78
	v_add_u32_e32 v198, s38, v248
	v_lshl_add_u64 v[202:203], s[70:71], 0, v[146:147]
	s_mov_b32 m0, s0
	ds_read_b128 v[186:189], v198
	ds_read_b128 v[190:193], v198 offset:1024
	ds_read_b128 v[194:197], v198 offset:2048
	ds_read_b128 v[198:201], v198 offset:3072
	global_load_lds_dwordx4 v[202:203], off
	v_lshl_add_u64 v[202:203], s[70:71], 0, v[152:153]
	s_add_i32 m0, s0, 0x2000
	s_nop 0
	global_load_lds_dwordx4 v[202:203], off
	s_barrier
	s_waitcnt lgkmcnt(0)
	s_setprio 1
	s_waitcnt lgkmcnt(0)
	v_mfma_f32_16x16x32_bf16 v[132:135], v[186:189], v[154:157], v[132:135]
	v_mfma_f32_16x16x32_bf16 v[128:131], v[194:197], v[154:157], v[128:131]
	v_mfma_f32_16x16x32_bf16 v[116:119], v[186:189], v[162:165], v[116:119]
	v_mfma_f32_16x16x32_bf16 v[112:115], v[194:197], v[162:165], v[112:115]
	v_mfma_f32_16x16x32_bf16 v[92:95], v[186:189], v[170:173], v[92:95]
	v_mfma_f32_16x16x32_bf16 v[80:83], v[194:197], v[170:173], v[80:83]
	v_mfma_f32_16x16x32_bf16 v[68:71], v[186:189], v[178:181], v[68:71]
	v_mfma_f32_16x16x32_bf16 v[64:67], v[194:197], v[178:181], v[64:67]
	v_mfma_f32_16x16x32_bf16 v[132:135], v[190:193], v[158:161], v[132:135]
	v_mfma_f32_16x16x32_bf16 v[128:131], v[198:201], v[158:161], v[128:131]
	v_mfma_f32_16x16x32_bf16 v[116:119], v[190:193], v[166:169], v[116:119]
	v_mfma_f32_16x16x32_bf16 v[112:115], v[198:201], v[166:169], v[112:115]
	v_mfma_f32_16x16x32_bf16 v[92:95], v[190:193], v[174:177], v[92:95]
	v_mfma_f32_16x16x32_bf16 v[80:83], v[198:201], v[174:177], v[80:83]
	v_mfma_f32_16x16x32_bf16 v[68:71], v[190:193], v[182:185], v[68:71]
	v_mfma_f32_16x16x32_bf16 v[64:67], v[198:201], v[182:185], v[64:67]
	s_setprio 0
	s_mov_b32 m0, s24
	v_lshl_add_u64 v[202:203], s[72:73], 0, v[148:149]
	s_barrier
	ds_read_b128 v[154:157], v249 offset:49152
	ds_read_b128 v[158:161], v249 offset:50176
	ds_read_b128 v[162:165], v249 offset:51200
	ds_read_b128 v[166:169], v249 offset:52224
	ds_read_b128 v[170:173], v249 offset:53248
	ds_read_b128 v[174:177], v249 offset:54272
	ds_read_b128 v[178:181], v249 offset:55296
	ds_read_b128 v[182:185], v249 offset:56320
	global_load_lds_dwordx4 v[202:203], off
	v_lshl_add_u64 v[202:203], s[72:73], 0, v[150:151]
	s_mov_b32 m0, s25
	s_nop 0
	global_load_lds_dwordx4 v[202:203], off
	s_barrier
; #define G_STAGE(bufoff, gbase, voff) do { _Pragma("unroll") for (int _i = 0; _i < 2; ++_i) \
;         __builtin_amdgcn_global_load_lds((const unsigned*)((const char*)(gbase) + (voff)[_i]), (LAS unsigned*)(lds + (bufoff) + ldsw + _i * 8192), 16, 0, 0); } while (0)
; #define G_MMA(ai, bj, At, Bt) do { __builtin_amdgcn_s_setprio(1); _Pragma("unroll") for (int m = 0; m < 4; ++m) _Pragma("unroll") for (int n = 0; n < 2; ++n) _Pragma("unroll") for (int k = 0; k < 2; ++k) \
;         acc[ai][bj][m][n] = __builtin_amdgcn_mfma_f32_16x16x32_bf16(Bt[n][k], At[m][k], acc[ai][bj][m][n], 0, 0, 0); __builtin_amdgcn_s_setprio(0); } while (0)
; #define G_WAIT_V(n) asm volatile("s_waitcnt vmcnt(" #n ")" ::: "memory")
; #define G_WAIT_L(n) asm volatile("s_waitcnt lgkmcnt(" #n ")" ::: "memory")
; #define G_BAR __builtin_amdgcn_s_barrier()
; #define G_SCHED __builtin_amdgcn_sched_barrier(0)
; template <class J>
; DI void gemm_phase(LAS unsigned char* lds, const J& job) {
;     ...
;       G_BAR; G_WAIT_L(0); G_MMA(1, 0, At, B0); G_BAR; G_SCHED;
;       G_STAGE(G_SB(1, 1), b3 + hstepB, voffB);
;       G_WAIT_V(6); G_BAR; G_MMA(1, 1, At, B1); G_BAR;
;   DI void epi(const Acc& acc, const Unit& u, int wr, int wc, int fr, int fq) const {
;     const int cc = u.pn * 64 + 16 * wc + 4 * fq;
;     u32x2 zz[2][4][4];
; #pragma unroll
;     for (int ai = 0; ai < 2; ++ai)
; #pragma unroll
;       for (int m = 0; m < 4; ++m) {
;         const u16* zr = Z + (size_t)(u.pm * 256 + ai * HALF + wr * 64 + m * 16 + fr) * NGATE + cc;
; #pragma unroll
;         for (int br = 0; br < 4; ++br) zz[ai][m][br] = *(const u32x2*)(zr + br * 2048);
;       }
;     f32x4 bg[4];
; #pragma unroll
;     for (int br = 0; br < 4; ++br) bg[br] = *(const f32x4*)(bgate + br * 2048 + cc);
	s_waitcnt lgkmcnt(0)
	s_setprio 1
	s_waitcnt lgkmcnt(0)
	v_mfma_f32_16x16x32_bf16 v[60:63], v[84:87], v[154:157], v[60:63]
	v_mfma_f32_16x16x32_bf16 v[56:59], v[96:99], v[154:157], v[56:59]
	v_mfma_f32_16x16x32_bf16 v[44:47], v[84:87], v[162:165], v[44:47]
	v_mfma_f32_16x16x32_bf16 v[40:43], v[96:99], v[162:165], v[40:43]
	v_mfma_f32_16x16x32_bf16 v[28:31], v[84:87], v[170:173], v[28:31]
	v_mfma_f32_16x16x32_bf16 v[24:27], v[96:99], v[170:173], v[24:27]
	v_mfma_f32_16x16x32_bf16 v[12:15], v[84:87], v[178:181], v[12:15]
	v_mfma_f32_16x16x32_bf16 v[8:11], v[96:99], v[178:181], v[8:11]
	v_mfma_f32_16x16x32_bf16 v[60:63], v[88:91], v[158:161], v[60:63]
	v_mfma_f32_16x16x32_bf16 v[56:59], v[100:103], v[158:161], v[56:59]
	v_mfma_f32_16x16x32_bf16 v[44:47], v[88:91], v[166:169], v[44:47]
	v_mfma_f32_16x16x32_bf16 v[40:43], v[100:103], v[166:169], v[40:43]
	v_mfma_f32_16x16x32_bf16 v[28:31], v[88:91], v[174:177], v[28:31]
	v_mfma_f32_16x16x32_bf16 v[24:27], v[100:103], v[174:177], v[24:27]
	v_mfma_f32_16x16x32_bf16 v[12:15], v[88:91], v[182:185], v[12:15]
	v_mfma_f32_16x16x32_bf16 v[8:11], v[100:103], v[182:185], v[8:11]
	s_setprio 0
	s_barrier
	s_add_u32 s0, s70, 0x1000000
	s_addc_u32 s1, s71, 0
	s_add_i32 s2, s38, s78
	v_lshl_add_u64 v[84:85], s[0:1], 0, v[146:147]
	s_mov_b32 m0, s2
	s_nop 0
	global_load_lds_dwordx4 v[84:85], off
	v_lshl_add_u64 v[84:85], s[0:1], 0, v[152:153]
	s_add_i32 m0, s2, 0x2000
	s_nop 0
	global_load_lds_dwordx4 v[84:85], off
	s_waitcnt vmcnt(6)
	s_barrier
	s_setprio 1
	v_mfma_f32_16x16x32_bf16 v[52:55], v[186:189], v[154:157], v[52:55]
	v_mfma_f32_16x16x32_bf16 v[48:51], v[194:197], v[154:157], v[48:51]
	v_mfma_f32_16x16x32_bf16 v[36:39], v[186:189], v[162:165], v[36:39]
	v_mfma_f32_16x16x32_bf16 v[32:35], v[194:197], v[162:165], v[32:35]
	v_mfma_f32_16x16x32_bf16 v[20:23], v[186:189], v[170:173], v[20:23]
	v_mfma_f32_16x16x32_bf16 v[16:19], v[194:197], v[170:173], v[16:19]
	v_mfma_f32_16x16x32_bf16 v[4:7], v[186:189], v[178:181], v[4:7]
	v_mfma_f32_16x16x32_bf16 v[0:3], v[194:197], v[178:181], v[0:3]
	v_mfma_f32_16x16x32_bf16 v[52:55], v[190:193], v[158:161], v[52:55]
	v_mfma_f32_16x16x32_bf16 v[48:51], v[198:201], v[158:161], v[48:51]
	v_mfma_f32_16x16x32_bf16 v[36:39], v[190:193], v[166:169], v[36:39]
	v_mfma_f32_16x16x32_bf16 v[32:35], v[198:201], v[166:169], v[32:35]
	v_mfma_f32_16x16x32_bf16 v[20:23], v[190:193], v[174:177], v[20:23]
	v_mfma_f32_16x16x32_bf16 v[16:19], v[198:201], v[174:177], v[16:19]
	v_mfma_f32_16x16x32_bf16 v[4:7], v[190:193], v[182:185], v[4:7]
	v_mfma_f32_16x16x32_bf16 v[0:3], v[198:201], v[182:185], v[0:3]
	s_setprio 0
	s_add_i32 s6, s6, 2
	s_addk_i32 s56, 0x100
	s_addk_i32 s7, 0x100
	s_cmp_gt_u32 s6, 29
	s_barrier
	s_cbranch_scc0 .LBB0_74
	v_mov_b32_e32 v84, v247
	v_mov_b32_e32 v85, v246
	s_lshl_b32 s0, s44, 6
	s_or_b32 s0, s0, s96
	v_lshl_add_u32 v84, v84, 2, s0
	s_lshl_b32 s0, s64, 8
	s_add_i32 s0, s0, s37
	v_add_u32_e32 v224, s0, v85
	v_ashrrev_i32_e32 v85, 31, v84
	v_lshlrev_b64 v[154:155], 1, v[84:85]
	v_ashrrev_i32_e32 v225, 31, v224
	v_lshl_add_u64 v[86:87], s[26:27], 0, v[154:155]
	v_lshlrev_b64 v[88:89], 14, v[224:225]
	v_lshl_add_u64 v[88:89], v[86:87], 0, v[88:89]
	v_add_co_u32_e32 v90, vcc, s82, v88
	v_add_u32_e32 v212, 16, v224
	s_nop 0
	v_addc_co_u32_e32 v91, vcc, 0, v89, vcc
	v_ashrrev_i32_e32 v213, 31, v212
	v_add_co_u32_e32 v96, vcc, s92, v88
	v_lshlrev_b64 v[98:99], 14, v[212:213]
	s_nop 0
	v_addc_co_u32_e32 v97, vcc, 0, v89, vcc
	v_lshl_add_u64 v[98:99], v[86:87], 0, v[98:99]
	v_add_co_u32_e32 v100, vcc, s82, v98
	v_add_u32_e32 v202, 32, v224
	s_nop 0
	v_addc_co_u32_e32 v101, vcc, 0, v99, vcc
	global_load_dwordx2 v[230:231], v[90:91], off offset:-4096
	global_load_dwordx2 v[226:227], v[90:91], off
	global_load_dwordx2 v[220:221], v[100:101], off offset:-4096
	global_load_dwordx2 v[214:215], v[100:101], off
	v_add_co_u32_e32 v90, vcc, s92, v98
	v_ashrrev_i32_e32 v203, 31, v202
	s_nop 0
	v_addc_co_u32_e32 v91, vcc, 0, v99, vcc
	global_load_dwordx2 v[232:233], v[88:89], off
	global_load_dwordx2 v[228:229], v[96:97], off
	global_load_dwordx2 v[222:223], v[98:99], off
	global_load_dwordx2 v[216:217], v[90:91], off
	v_lshlrev_b64 v[88:89], 14, v[202:203]
	v_lshl_add_u64 v[88:89], v[86:87], 0, v[88:89]
	v_add_co_u32_e32 v90, vcc, s82, v88
	v_add_u32_e32 v190, 48, v224
	s_nop 0
	v_addc_co_u32_e32 v91, vcc, 0, v89, vcc
	v_ashrrev_i32_e32 v191, 31, v190
	v_add_co_u32_e32 v96, vcc, s92, v88
	v_lshlrev_b64 v[98:99], 14, v[190:191]
	s_nop 0
	v_addc_co_u32_e32 v97, vcc, 0, v89, vcc
	v_lshl_add_u64 v[98:99], v[86:87], 0, v[98:99]
	v_add_co_u32_e32 v100, vcc, s82, v98
	v_add_u32_e32 v184, 0x80, v224
	s_nop 0
	v_addc_co_u32_e32 v101, vcc, 0, v99, vcc
	global_load_dwordx2 v[210:211], v[90:91], off offset:-4096
	global_load_dwordx2 v[206:207], v[90:91], off
	global_load_dwordx2 v[200:201], v[100:101], off offset:-4096
	global_load_dwordx2 v[192:193], v[100:101], off
	v_add_co_u32_e32 v90, vcc, s92, v98
	v_lshl_add_u64 v[84:85], v[84:85], 2, s[12:13]
	v_ashrrev_i32_e32 v185, 31, v184
	v_addc_co_u32_e32 v91, vcc, 0, v99, vcc
	global_load_dwordx4 v[100:103], v[84:85], off
	global_load_dwordx2 v[218:219], v[88:89], off
	global_load_dwordx2 v[208:209], v[96:97], off
	global_load_dwordx2 v[204:205], v[98:99], off
	global_load_dwordx2 v[198:199], v[90:91], off
	v_lshlrev_b64 v[88:89], 14, v[184:185]
	v_lshl_add_u64 v[88:89], v[86:87], 0, v[88:89]
	v_add_co_u32_e32 v90, vcc, s82, v88
	v_add_u32_e32 v174, 0x90, v224
	s_nop 0
	v_addc_co_u32_e32 v91, vcc, 0, v89, vcc
	v_add_co_u32_e32 v156, vcc, s92, v88
	v_ashrrev_i32_e32 v175, 31, v174
	s_nop 0
	v_addc_co_u32_e32 v157, vcc, 0, v89, vcc
; DI float bflo(unsigned u) { return __uint_as_float(u << 16); }
; DI float bfhi(unsigned u) { return __uint_as_float(u & 0xffff0000u); }
; DI float sigm(float x) { return __builtin_amdgcn_rcpf(1.f + __expf(-x)); }
;   DI void epi(const Acc& acc, const Unit& u, int wr, int wc, int fr, int fq) const {
;     ...
;         const u16* zr = Z + (size_t)(u.pm * 256 + ai * HALF + wr * 64 + m * 16 + fr) * NGATE + cc;
; #pragma unroll
;         for (int br = 0; br < 4; ++br) zz[ai][m][br] = *(const u32x2*)(zr + br * 2048);
;       }
;     f32x4 bg[4];
; #pragma unroll
;     for (int br = 0; br < 4; ++br) bg[br] = *(const f32x4*)(bgate + br * 2048 + cc);
;     ...
;     for (int ai = 0; ai < 2; ++ai)
; #pragma unroll
;       for (int m = 0; m < 4; ++m) {
;         const int row = u.pm * 256 + ai * HALF + wr * 64 + m * 16 + fr;
;         f32x4 sum = {0.f, 0.f, 0.f, 0.f};
; #pragma unroll
;         for (int bj = 0; bj < 2; ++bj)
; #pragma unroll
;           for (int n = 0; n < 2; ++n) {
;             const int br = 2 * bj + n;
;             const f32x4 v = acc[ai][bj][m][n] + bg[br];
;             const u32x2 z = zz[ai][m][br];
;             sum.x += sigm(v.x) * bflo(z.x); sum.y += sigm(v.y) * bfhi(z.x); sum.z += sigm(v.z) * bflo(z.y); sum.w += sigm(v.w) * bfhi(z.y);
	v_add_co_u32_e32 v96, vcc, s82, v84
	v_lshlrev_b64 v[158:159], 14, v[174:175]
	s_nop 0
	v_addc_co_u32_e32 v97, vcc, 0, v85, vcc
	global_load_dwordx4 v[96:99], v[96:97], off
	v_lshl_add_u64 v[158:159], v[86:87], 0, v[158:159]
	v_add_co_u32_e32 v160, vcc, s82, v158
	v_add_u32_e32 v164, 0xa0, v224
	s_nop 0
	v_addc_co_u32_e32 v161, vcc, 0, v159, vcc
	global_load_dwordx2 v[194:195], v[90:91], off offset:-4096
	global_load_dwordx2 v[186:187], v[90:91], off
	global_load_dwordx2 v[180:181], v[160:161], off offset:-4096
	global_load_dwordx2 v[176:177], v[160:161], off
	v_add_co_u32_e32 v90, vcc, s92, v158
	v_ashrrev_i32_e32 v165, 31, v164
	s_nop 0
	v_addc_co_u32_e32 v91, vcc, 0, v159, vcc
	global_load_dwordx2 v[196:197], v[88:89], off
	global_load_dwordx2 v[188:189], v[156:157], off
	global_load_dwordx2 v[182:183], v[158:159], off
	global_load_dwordx2 v[178:179], v[90:91], off
	v_lshlrev_b64 v[88:89], 14, v[164:165]
	v_lshl_add_u64 v[162:163], v[86:87], 0, v[88:89]
	v_add_co_u32_e32 v158, vcc, s82, v162
	v_add_u32_e32 v156, 0xb0, v224
	s_nop 0
	v_addc_co_u32_e32 v159, vcc, 0, v163, vcc
	v_add_co_u32_e32 v168, vcc, s92, v162
	v_ashrrev_i32_e32 v157, 31, v156
	s_nop 0
	v_addc_co_u32_e32 v169, vcc, 0, v163, vcc
	v_add_co_u32_e32 v88, vcc, s54, v84
	v_lshlrev_b64 v[160:161], 14, v[156:157]
	s_nop 0
	v_addc_co_u32_e32 v89, vcc, 0, v85, vcc
	global_load_dwordx4 v[88:91], v[88:89], off
	v_lshl_add_u64 v[250:251], v[86:87], 0, v[160:161]
	v_add_co_u32_e32 v86, vcc, s82, v250
	s_mov_b32 s44, s20
	s_nop 0
	v_addc_co_u32_e32 v87, vcc, 0, v251, vcc
	v_add_co_u32_e32 v84, vcc, s55, v84
	global_load_dwordx2 v[170:171], v[158:159], off offset:-4096
	global_load_dwordx2 v[166:167], v[158:159], off
	global_load_dwordx2 v[160:161], v[86:87], off offset:-4096
	s_nop 0
	global_load_dwordx2 v[158:159], v[86:87], off
	v_addc_co_u32_e32 v85, vcc, 0, v85, vcc
	global_load_dwordx4 v[84:87], v[84:85], off
	v_add_co_u32_e32 v252, vcc, s92, v250
	s_mov_b32 s64, s18
	s_nop 0
	v_addc_co_u32_e32 v253, vcc, 0, v251, vcc
	s_and_b64 vcc, exec, s[8:9]
	s_mov_b64 s[66:67], s[62:63]
	s_mov_b64 s[68:69], s[22:23]
	v_readlane_b32 s0, v255, 23
	s_cmpk_gt_u32 s0, 0xff
	s_cbranch_scc1 .Lds_gate_x
	s_barrier
.Lds_gate_x:
	s_waitcnt vmcnt(0)
	v_pk_add_f32 v[236:237], v[140:141], v[100:101]
	s_nop 0
	v_mul_f32_e32 v140, 0xbfb8aa3b, v236
	v_pk_add_f32 v[142:143], v[142:143], v[102:103]
	v_exp_f32_e32 v236, v140
	v_mul_f32_e32 v237, 0xbfb8aa3b, v237
	v_mul_f32_e32 v142, 0xbfb8aa3b, v142
	global_load_dwordx2 v[172:173], v[162:163], off
	s_nop 0
	global_load_dwordx2 v[168:169], v[168:169], off
	s_nop 0
	global_load_dwordx2 v[162:163], v[250:251], off
	global_load_dwordx2 v[140:141], v[252:253], off
	v_exp_f32_e32 v237, v237
	v_exp_f32_e32 v250, v142
	v_add_f32_e32 v236, 1.0, v236
	v_rcp_f32_e32 v142, v236
	v_add_f32_e32 v236, 1.0, v237
	v_add_f32_e32 v237, 1.0, v250
	v_mul_f32_e32 v143, 0xbfb8aa3b, v143
	v_rcp_f32_e32 v250, v237
	v_exp_f32_e32 v143, v143
	v_rcp_f32_e32 v236, v236
	v_lshlrev_b32_e32 v253, 16, v230
	v_lshlrev_b32_e32 v252, 16, v232
	v_pk_add_f32 v[124:125], v[124:125], v[100:101]
	v_pk_add_f32 v[126:127], v[126:127], v[102:103]
	v_mul_f32_e32 v125, 0xbfb8aa3b, v125
	v_pk_add_f32 v[136:137], v[136:137], v[96:97]
	v_pk_add_f32 v[138:139], v[138:139], v[98:99]
	v_mul_f32_e32 v137, 0xbfb8aa3b, v137
	v_mul_f32_e32 v136, 0xbfb8aa3b, v136
	v_exp_f32_e32 v137, v137
	v_exp_f32_e32 v237, v136
	v_add_f32_e32 v136, 1.0, v143
	v_rcp_f32_e32 v136, v136
	v_add_f32_e32 v137, 1.0, v137
	v_add_f32_e32 v143, 1.0, v237
	v_rcp_f32_e32 v237, v137
	v_mul_f32_e32 v137, 0xbfb8aa3b, v138
	v_exp_f32_e32 v137, v137
	v_rcp_f32_e32 v143, v143
	v_exp_f32_e32 v125, v125
	v_mul_f32_e32 v126, 0xbfb8aa3b, v126
	v_add_f32_e32 v137, 1.0, v137
	v_rcp_f32_e32 v251, v137
	v_mul_f32_e32 v137, 0xbfb8aa3b, v139
	v_pk_mul_f32 v[142:143], v[142:143], v[252:253]
	v_exp_f32_e32 v137, v137
	v_add_f32_e32 v142, 0, v142
	v_add_f32_e32 v252, v142, v143
	v_and_b32_e32 v143, 0xffff0000, v230
	v_and_b32_e32 v142, 0xffff0000, v232
	v_pk_mul_f32 v[142:143], v[236:237], v[142:143]
	v_add_f32_e32 v137, 1.0, v137
	v_add_f32_e32 v138, 0, v142
	v_add_f32_e32 v230, v138, v143
	v_lshlrev_b32_e32 v143, 16, v231
	v_lshlrev_b32_e32 v142, 16, v233
	v_rcp_f32_e32 v137, v137
	v_pk_mul_f32 v[138:139], v[250:251], v[142:143]
	v_pk_add_f32 v[132:133], v[132:133], v[88:89]
	v_add_f32_e32 v138, 0, v138
	v_add_f32_e32 v142, v138, v139
	v_and_b32_e32 v139, 0xffff0000, v231
	v_and_b32_e32 v138, 0xffff0000, v233
	v_pk_mul_f32 v[136:137], v[136:137], v[138:139]
	v_pk_add_f32 v[134:135], v[134:135], v[90:91]
	v_mul_f32_e32 v133, 0xbfb8aa3b, v133
	v_add_f32_e32 v136, 0, v136
	v_exp_f32_e32 v133, v133
	v_mul_f32_e32 v134, 0xbfb8aa3b, v134
	v_add_f32_e32 v143, v136, v137
	v_exp_f32_e32 v136, v134
	v_add_f32_e32 v133, 1.0, v133
	v_pk_add_f32 v[128:129], v[128:129], v[84:85]
	v_rcp_f32_e32 v134, v133
	v_add_f32_e32 v133, 1.0, v136
	v_mul_f32_e32 v129, 0xbfb8aa3b, v129
	v_rcp_f32_e32 v136, v133
	v_mul_f32_e32 v133, 0xbfb8aa3b, v135
	v_mul_f32_e32 v128, 0xbfb8aa3b, v128
	v_exp_f32_e32 v129, v129
	v_exp_f32_e32 v133, v133
	v_exp_f32_e32 v135, v128
	v_mul_f32_e32 v132, 0xbfb8aa3b, v132
	v_exp_f32_e32 v132, v132
	v_pk_add_f32 v[130:131], v[130:131], v[86:87]
	v_add_f32_e32 v129, 1.0, v129
	v_add_f32_e32 v128, 1.0, v133
	v_add_f32_e32 v133, 1.0, v135
	v_rcp_f32_e32 v135, v129
	v_mul_f32_e32 v129, 0xbfb8aa3b, v130
	v_exp_f32_e32 v129, v129
	v_add_f32_e32 v132, 1.0, v132
	v_rcp_f32_e32 v132, v132
	v_rcp_f32_e32 v133, v133
	v_add_f32_e32 v129, 1.0, v129
	v_lshlrev_b32_e32 v139, 16, v228
	v_lshlrev_b32_e32 v138, 16, v226
	v_rcp_f32_e32 v137, v129
	v_mul_f32_e32 v129, 0xbfb8aa3b, v131
; DI unsigned pk2(float lo, float hi) { unsigned r; asm("v_cvt_pk_bf16_f32 %0, %1, %2" : "=v"(r) : "v"(lo), "v"(hi)); return r; }
; DI float bflo(unsigned u) { return __uint_as_float(u << 16); }
; DI float bfhi(unsigned u) { return __uint_as_float(u & 0xffff0000u); }
; DI float sigm(float x) { return __builtin_amdgcn_rcpf(1.f + __expf(-x)); }
;   DI void epi(const Acc& acc, const Unit& u, int wr, int wc, int fr, int fq) const {
;     ...
;     for (int ai = 0; ai < 2; ++ai)
; #pragma unroll
;       for (int m = 0; m < 4; ++m) {
;         const int row = u.pm * 256 + ai * HALF + wr * 64 + m * 16 + fr;
;         f32x4 sum = {0.f, 0.f, 0.f, 0.f};
; #pragma unroll
;         for (int bj = 0; bj < 2; ++bj)
; #pragma unroll
;           for (int n = 0; n < 2; ++n) {
;             const int br = 2 * bj + n;
;             const f32x4 v = acc[ai][bj][m][n] + bg[br];
;             const u32x2 z = zz[ai][m][br];
;             sum.x += sigm(v.x) * bflo(z.x); sum.y += sigm(v.y) * bfhi(z.x); sum.z += sigm(v.z) * bflo(z.y); sum.w += sigm(v.w) * bfhi(z.y);
;           }
;         u32x2 o; o.x = pk2(sum.x, sum.y); o.y = pk2(sum.z, sum.w);
;         *(u32x2*)(mixed + (size_t)row * DM + cc) = o;
	v_pk_mul_f32 v[132:133], v[132:133], v[138:139]
	v_exp_f32_e32 v129, v129
	v_add_f32_e32 v132, v252, v132
	v_add_f32_e32 v138, v132, v133
	v_and_b32_e32 v133, 0xffff0000, v228
	v_and_b32_e32 v132, 0xffff0000, v226
	v_pk_mul_f32 v[132:133], v[134:135], v[132:133]
	v_add_f32_e32 v129, 1.0, v129
	v_add_f32_e32 v130, v230, v132
	v_rcp_f32_e32 v128, v128
	v_add_f32_e32 v134, v130, v133
	v_lshlrev_b32_e32 v133, 16, v229
	v_lshlrev_b32_e32 v132, 16, v227
	v_rcp_f32_e32 v129, v129
	v_pk_mul_f32 v[130:131], v[136:137], v[132:133]
	v_add_f32_e32 v125, 1.0, v125
	v_add_f32_e32 v130, v142, v130
	v_add_f32_e32 v132, v130, v131
	v_and_b32_e32 v131, 0xffff0000, v229
	v_and_b32_e32 v130, 0xffff0000, v227
	v_pk_mul_f32 v[128:129], v[128:129], v[130:131]
	v_lshlrev_b64 v[130:131], 12, v[224:225]
	v_add_f32_e32 v128, v143, v128
	v_lshl_add_u64 v[130:131], s[10:11], 0, v[130:131]
	v_add_f32_e32 v129, v128, v129
	v_cvt_pk_bf16_f32 v128, v138, v134
	v_lshl_add_u64 v[130:131], v[130:131], 0, v[154:155]
	v_cvt_pk_bf16_f32 v129, v132, v129
	global_store_dwordx2 v[130:131], v[128:129], off
	v_exp_f32_e32 v128, v126
	v_pk_add_f32 v[120:121], v[120:121], v[96:97]
	v_rcp_f32_e32 v126, v125
	v_mul_f32_e32 v121, 0xbfb8aa3b, v121
	v_add_f32_e32 v125, 1.0, v128
	v_rcp_f32_e32 v128, v125
	v_mul_f32_e32 v125, 0xbfb8aa3b, v127
	v_mul_f32_e32 v120, 0xbfb8aa3b, v120
	v_exp_f32_e32 v121, v121
	v_exp_f32_e32 v125, v125
	v_exp_f32_e32 v127, v120
	v_mul_f32_e32 v124, 0xbfb8aa3b, v124
	v_exp_f32_e32 v124, v124
	v_pk_add_f32 v[122:123], v[122:123], v[98:99]
	v_add_f32_e32 v121, 1.0, v121
	v_add_f32_e32 v120, 1.0, v125
	v_add_f32_e32 v125, 1.0, v127
	v_rcp_f32_e32 v127, v121
	v_mul_f32_e32 v121, 0xbfb8aa3b, v122
	v_exp_f32_e32 v121, v121
	v_add_f32_e32 v124, 1.0, v124
	v_rcp_f32_e32 v124, v124
	v_rcp_f32_e32 v125, v125
	v_add_f32_e32 v121, 1.0, v121
	v_lshlrev_b32_e32 v131, 16, v220
	v_lshlrev_b32_e32 v130, 16, v222
	v_rcp_f32_e32 v129, v121
	v_mul_f32_e32 v121, 0xbfb8aa3b, v123
	v_pk_mul_f32 v[124:125], v[124:125], v[130:131]
	v_exp_f32_e32 v121, v121
	v_add_f32_e32 v124, 0, v124
	v_add_f32_e32 v130, v124, v125
	v_and_b32_e32 v125, 0xffff0000, v220
	v_and_b32_e32 v124, 0xffff0000, v222
	v_pk_mul_f32 v[124:125], v[126:127], v[124:125]
	v_add_f32_e32 v121, 1.0, v121
	v_add_f32_e32 v122, 0, v124
	v_rcp_f32_e32 v120, v120
	v_add_f32_e32 v126, v122, v125
	v_lshlrev_b32_e32 v125, 16, v221
	v_lshlrev_b32_e32 v124, 16, v223
	v_rcp_f32_e32 v121, v121
	v_pk_mul_f32 v[122:123], v[128:129], v[124:125]
	v_pk_add_f32 v[116:117], v[116:117], v[88:89]
	v_add_f32_e32 v122, 0, v122
	v_add_f32_e32 v124, v122, v123
	v_and_b32_e32 v123, 0xffff0000, v221
	v_and_b32_e32 v122, 0xffff0000, v223
	v_pk_mul_f32 v[120:121], v[120:121], v[122:123]
	v_pk_add_f32 v[118:119], v[118:119], v[90:91]
	v_mul_f32_e32 v117, 0xbfb8aa3b, v117
	v_add_f32_e32 v120, 0, v120
	v_exp_f32_e32 v117, v117
	v_mul_f32_e32 v118, 0xbfb8aa3b, v118
	v_add_f32_e32 v125, v120, v121
	v_exp_f32_e32 v120, v118
	v_add_f32_e32 v117, 1.0, v117
	v_pk_add_f32 v[112:113], v[112:113], v[84:85]
	v_rcp_f32_e32 v118, v117
	v_add_f32_e32 v117, 1.0, v120
	v_mul_f32_e32 v113, 0xbfb8aa3b, v113
	v_rcp_f32_e32 v120, v117
	v_mul_f32_e32 v117, 0xbfb8aa3b, v119
	v_mul_f32_e32 v112, 0xbfb8aa3b, v112
	v_exp_f32_e32 v113, v113
	v_exp_f32_e32 v117, v117
	v_exp_f32_e32 v119, v112
	v_mul_f32_e32 v116, 0xbfb8aa3b, v116
	v_exp_f32_e32 v116, v116
	v_pk_add_f32 v[114:115], v[114:115], v[86:87]
	v_add_f32_e32 v113, 1.0, v113
	v_add_f32_e32 v112, 1.0, v117
	v_add_f32_e32 v117, 1.0, v119
	v_rcp_f32_e32 v119, v113
	v_mul_f32_e32 v113, 0xbfb8aa3b, v114
	v_exp_f32_e32 v113, v113
	v_add_f32_e32 v116, 1.0, v116
	v_rcp_f32_e32 v116, v116
	v_rcp_f32_e32 v117, v117
	v_add_f32_e32 v113, 1.0, v113
	v_lshlrev_b32_e32 v123, 16, v216
	v_lshlrev_b32_e32 v122, 16, v214
	v_rcp_f32_e32 v121, v113
	v_mul_f32_e32 v113, 0xbfb8aa3b, v115
	v_pk_mul_f32 v[116:117], v[116:117], v[122:123]
	v_exp_f32_e32 v113, v113
	v_add_f32_e32 v116, v130, v116
	v_add_f32_e32 v122, v116, v117
	v_and_b32_e32 v117, 0xffff0000, v216
	v_and_b32_e32 v116, 0xffff0000, v214
	v_pk_mul_f32 v[116:117], v[118:119], v[116:117]
	v_add_f32_e32 v113, 1.0, v113
	v_add_f32_e32 v114, v126, v116
	v_rcp_f32_e32 v112, v112
	v_add_f32_e32 v118, v114, v117
	v_lshlrev_b32_e32 v117, 16, v217
	v_lshlrev_b32_e32 v116, 16, v215
	v_rcp_f32_e32 v113, v113
	v_pk_mul_f32 v[114:115], v[120:121], v[116:117]
	v_pk_add_f32 v[108:109], v[108:109], v[100:101]
	v_add_f32_e32 v114, v124, v114
	v_add_f32_e32 v116, v114, v115
	v_and_b32_e32 v115, 0xffff0000, v217
	v_and_b32_e32 v114, 0xffff0000, v215
	v_pk_mul_f32 v[112:113], v[112:113], v[114:115]
	v_lshlrev_b64 v[114:115], 12, v[212:213]
	v_add_f32_e32 v112, v125, v112
	v_lshl_add_u64 v[114:115], s[10:11], 0, v[114:115]
	v_pk_add_f32 v[110:111], v[110:111], v[102:103]
	v_mul_f32_e32 v109, 0xbfb8aa3b, v109
	v_add_f32_e32 v113, v112, v113
	v_cvt_pk_bf16_f32 v112, v122, v118
	v_lshl_add_u64 v[114:115], v[114:115], 0, v[154:155]
	v_exp_f32_e32 v109, v109
	v_mul_f32_e32 v110, 0xbfb8aa3b, v110
	v_cvt_pk_bf16_f32 v113, v116, v113
	global_store_dwordx2 v[114:115], v[112:113], off
	v_exp_f32_e32 v112, v110
	v_add_f32_e32 v109, 1.0, v109
	v_pk_add_f32 v[104:105], v[104:105], v[96:97]
	v_rcp_f32_e32 v110, v109
	v_add_f32_e32 v109, 1.0, v112
	v_mul_f32_e32 v105, 0xbfb8aa3b, v105
	v_rcp_f32_e32 v112, v109
	v_mul_f32_e32 v109, 0xbfb8aa3b, v111
	v_mul_f32_e32 v104, 0xbfb8aa3b, v104
	v_exp_f32_e32 v105, v105
	v_exp_f32_e32 v109, v109
	v_exp_f32_e32 v111, v104
	v_mul_f32_e32 v108, 0xbfb8aa3b, v108
	v_exp_f32_e32 v108, v108
	v_pk_add_f32 v[106:107], v[106:107], v[98:99]
	v_add_f32_e32 v105, 1.0, v105
; DI unsigned pk2(float lo, float hi) { unsigned r; asm("v_cvt_pk_bf16_f32 %0, %1, %2" : "=v"(r) : "v"(lo), "v"(hi)); return r; }
; DI float bflo(unsigned u) { return __uint_as_float(u << 16); }
; DI float bfhi(unsigned u) { return __uint_as_float(u & 0xffff0000u); }
; DI float sigm(float x) { return __builtin_amdgcn_rcpf(1.f + __expf(-x)); }
;   DI void epi(const Acc& acc, const Unit& u, int wr, int wc, int fr, int fq) const {
;     ...
;     for (int ai = 0; ai < 2; ++ai)
; #pragma unroll
;       for (int m = 0; m < 4; ++m) {
;         const int row = u.pm * 256 + ai * HALF + wr * 64 + m * 16 + fr;
;         f32x4 sum = {0.f, 0.f, 0.f, 0.f};
; #pragma unroll
;         for (int bj = 0; bj < 2; ++bj)
; #pragma unroll
;           for (int n = 0; n < 2; ++n) {
;             const int br = 2 * bj + n;
;             const f32x4 v = acc[ai][bj][m][n] + bg[br];
;             const u32x2 z = zz[ai][m][br];
;             sum.x += sigm(v.x) * bflo(z.x); sum.y += sigm(v.y) * bfhi(z.x); sum.z += sigm(v.z) * bflo(z.y); sum.w += sigm(v.w) * bfhi(z.y);
;           }
;         u32x2 o; o.x = pk2(sum.x, sum.y); o.y = pk2(sum.z, sum.w);
;         *(u32x2*)(mixed + (size_t)row * DM + cc) = o;
	v_add_f32_e32 v104, 1.0, v109
	v_add_f32_e32 v109, 1.0, v111
	v_rcp_f32_e32 v111, v105
	v_mul_f32_e32 v105, 0xbfb8aa3b, v106
	v_exp_f32_e32 v105, v105
	v_add_f32_e32 v108, 1.0, v108
	v_rcp_f32_e32 v108, v108
	v_rcp_f32_e32 v109, v109
	v_add_f32_e32 v105, 1.0, v105
	v_lshlrev_b32_e32 v115, 16, v210
	v_lshlrev_b32_e32 v114, 16, v218
	v_rcp_f32_e32 v113, v105
	v_mul_f32_e32 v105, 0xbfb8aa3b, v107
	v_pk_mul_f32 v[108:109], v[108:109], v[114:115]
	v_exp_f32_e32 v105, v105
	v_add_f32_e32 v108, 0, v108
	v_add_f32_e32 v114, v108, v109
	v_and_b32_e32 v109, 0xffff0000, v210
	v_and_b32_e32 v108, 0xffff0000, v218
	v_pk_mul_f32 v[108:109], v[110:111], v[108:109]
	v_add_f32_e32 v105, 1.0, v105
	v_add_f32_e32 v106, 0, v108
	v_rcp_f32_e32 v104, v104
	v_add_f32_e32 v110, v106, v109
	v_lshlrev_b32_e32 v109, 16, v211
	v_lshlrev_b32_e32 v108, 16, v219
	v_rcp_f32_e32 v105, v105
	v_pk_mul_f32 v[106:107], v[112:113], v[108:109]
	v_pk_add_f32 v[92:93], v[92:93], v[88:89]
	v_add_f32_e32 v106, 0, v106
	v_add_f32_e32 v108, v106, v107
	v_and_b32_e32 v107, 0xffff0000, v211
	v_and_b32_e32 v106, 0xffff0000, v219
	v_pk_mul_f32 v[104:105], v[104:105], v[106:107]
	v_pk_add_f32 v[94:95], v[94:95], v[90:91]
	v_mul_f32_e32 v93, 0xbfb8aa3b, v93
	v_add_f32_e32 v104, 0, v104
	v_exp_f32_e32 v93, v93
	v_mul_f32_e32 v94, 0xbfb8aa3b, v94
	v_add_f32_e32 v109, v104, v105
	v_exp_f32_e32 v104, v94
	v_add_f32_e32 v93, 1.0, v93
	v_pk_add_f32 v[80:81], v[80:81], v[84:85]
	v_rcp_f32_e32 v94, v93
	v_add_f32_e32 v93, 1.0, v104
	v_mul_f32_e32 v81, 0xbfb8aa3b, v81
	v_rcp_f32_e32 v104, v93
	v_mul_f32_e32 v93, 0xbfb8aa3b, v95
	v_mul_f32_e32 v80, 0xbfb8aa3b, v80
	v_exp_f32_e32 v81, v81
	v_exp_f32_e32 v93, v93
	v_exp_f32_e32 v95, v80
	v_mul_f32_e32 v92, 0xbfb8aa3b, v92
	v_exp_f32_e32 v92, v92
	v_pk_add_f32 v[82:83], v[82:83], v[86:87]
	v_add_f32_e32 v81, 1.0, v81
	v_add_f32_e32 v80, 1.0, v93
	v_add_f32_e32 v93, 1.0, v95
	v_rcp_f32_e32 v95, v81
	v_mul_f32_e32 v81, 0xbfb8aa3b, v82
	v_exp_f32_e32 v81, v81
	v_add_f32_e32 v92, 1.0, v92
	v_rcp_f32_e32 v92, v92
	v_rcp_f32_e32 v93, v93
	v_add_f32_e32 v81, 1.0, v81
	v_lshlrev_b32_e32 v107, 16, v208
	v_lshlrev_b32_e32 v106, 16, v206
	v_rcp_f32_e32 v105, v81
	v_mul_f32_e32 v81, 0xbfb8aa3b, v83
	v_pk_mul_f32 v[92:93], v[92:93], v[106:107]
	v_exp_f32_e32 v81, v81
	v_add_f32_e32 v92, v114, v92
	v_add_f32_e32 v106, v92, v93
	v_and_b32_e32 v93, 0xffff0000, v208
	v_and_b32_e32 v92, 0xffff0000, v206
	v_pk_mul_f32 v[92:93], v[94:95], v[92:93]
	v_add_f32_e32 v81, 1.0, v81
	v_add_f32_e32 v82, v110, v92
	v_rcp_f32_e32 v80, v80
	v_add_f32_e32 v94, v82, v93
	v_lshlrev_b32_e32 v93, 16, v209
	v_lshlrev_b32_e32 v92, 16, v207
	v_rcp_f32_e32 v81, v81
	v_pk_mul_f32 v[82:83], v[104:105], v[92:93]
	v_pk_add_f32 v[76:77], v[76:77], v[100:101]
	v_add_f32_e32 v82, v108, v82
	v_add_f32_e32 v92, v82, v83
	v_and_b32_e32 v83, 0xffff0000, v209
	v_and_b32_e32 v82, 0xffff0000, v207
	v_pk_mul_f32 v[80:81], v[80:81], v[82:83]
	v_lshlrev_b64 v[82:83], 12, v[202:203]
	v_add_f32_e32 v80, v109, v80
	v_lshl_add_u64 v[82:83], s[10:11], 0, v[82:83]
	v_pk_add_f32 v[78:79], v[78:79], v[102:103]
	v_mul_f32_e32 v77, 0xbfb8aa3b, v77
	v_add_f32_e32 v81, v80, v81
	v_cvt_pk_bf16_f32 v80, v106, v94
	v_lshl_add_u64 v[82:83], v[82:83], 0, v[154:155]
	v_exp_f32_e32 v77, v77
	v_mul_f32_e32 v78, 0xbfb8aa3b, v78
	v_cvt_pk_bf16_f32 v81, v92, v81
	global_store_dwordx2 v[82:83], v[80:81], off
	v_exp_f32_e32 v80, v78
	v_add_f32_e32 v77, 1.0, v77
	v_pk_add_f32 v[72:73], v[72:73], v[96:97]
	v_rcp_f32_e32 v78, v77
	v_add_f32_e32 v77, 1.0, v80
	v_mul_f32_e32 v73, 0xbfb8aa3b, v73
	v_rcp_f32_e32 v80, v77
	v_mul_f32_e32 v77, 0xbfb8aa3b, v79
	v_mul_f32_e32 v72, 0xbfb8aa3b, v72
	v_exp_f32_e32 v73, v73
	v_exp_f32_e32 v77, v77
	v_exp_f32_e32 v79, v72
	v_mul_f32_e32 v76, 0xbfb8aa3b, v76
	v_exp_f32_e32 v76, v76
	v_pk_add_f32 v[74:75], v[74:75], v[98:99]
	v_add_f32_e32 v73, 1.0, v73
	v_add_f32_e32 v72, 1.0, v77
	v_add_f32_e32 v77, 1.0, v79
	v_rcp_f32_e32 v79, v73
	v_mul_f32_e32 v73, 0xbfb8aa3b, v74
	v_exp_f32_e32 v73, v73
	v_add_f32_e32 v76, 1.0, v76
	v_rcp_f32_e32 v76, v76
	v_rcp_f32_e32 v77, v77
	v_add_f32_e32 v73, 1.0, v73
	v_lshlrev_b32_e32 v83, 16, v200
	v_lshlrev_b32_e32 v82, 16, v204
	v_rcp_f32_e32 v81, v73
	v_mul_f32_e32 v73, 0xbfb8aa3b, v75
	v_pk_mul_f32 v[76:77], v[76:77], v[82:83]
	v_exp_f32_e32 v73, v73
	v_add_f32_e32 v76, 0, v76
	v_add_f32_e32 v82, v76, v77
	v_and_b32_e32 v77, 0xffff0000, v200
	v_and_b32_e32 v76, 0xffff0000, v204
	v_pk_mul_f32 v[76:77], v[78:79], v[76:77]
	v_add_f32_e32 v73, 1.0, v73
	v_add_f32_e32 v74, 0, v76
	v_rcp_f32_e32 v72, v72
	v_add_f32_e32 v78, v74, v77
	v_lshlrev_b32_e32 v77, 16, v201
	v_lshlrev_b32_e32 v76, 16, v205
	v_rcp_f32_e32 v73, v73
	v_pk_mul_f32 v[74:75], v[80:81], v[76:77]
	v_pk_add_f32 v[68:69], v[68:69], v[88:89]
	v_add_f32_e32 v74, 0, v74
	v_add_f32_e32 v76, v74, v75
	v_and_b32_e32 v75, 0xffff0000, v201
	v_and_b32_e32 v74, 0xffff0000, v205
	v_pk_mul_f32 v[72:73], v[72:73], v[74:75]
	v_pk_add_f32 v[70:71], v[70:71], v[90:91]
	v_mul_f32_e32 v69, 0xbfb8aa3b, v69
	v_add_f32_e32 v72, 0, v72
	v_exp_f32_e32 v69, v69
	v_mul_f32_e32 v70, 0xbfb8aa3b, v70
	v_add_f32_e32 v77, v72, v73
	v_exp_f32_e32 v72, v70
	v_add_f32_e32 v69, 1.0, v69
	v_pk_add_f32 v[64:65], v[64:65], v[84:85]
	v_rcp_f32_e32 v70, v69
	v_add_f32_e32 v69, 1.0, v72
	v_mul_f32_e32 v65, 0xbfb8aa3b, v65
	v_rcp_f32_e32 v72, v69
	v_mul_f32_e32 v69, 0xbfb8aa3b, v71
	v_mul_f32_e32 v64, 0xbfb8aa3b, v64
	v_exp_f32_e32 v65, v65
	v_exp_f32_e32 v69, v69
	v_exp_f32_e32 v71, v64
	v_mul_f32_e32 v68, 0xbfb8aa3b, v68
	v_exp_f32_e32 v68, v68
	v_pk_add_f32 v[66:67], v[66:67], v[86:87]
	v_add_f32_e32 v65, 1.0, v65
	v_add_f32_e32 v64, 1.0, v69
; DI unsigned pk2(float lo, float hi) { unsigned r; asm("v_cvt_pk_bf16_f32 %0, %1, %2" : "=v"(r) : "v"(lo), "v"(hi)); return r; }
; DI float bflo(unsigned u) { return __uint_as_float(u << 16); }
; DI float bfhi(unsigned u) { return __uint_as_float(u & 0xffff0000u); }
; DI float sigm(float x) { return __builtin_amdgcn_rcpf(1.f + __expf(-x)); }
;   DI void epi(const Acc& acc, const Unit& u, int wr, int wc, int fr, int fq) const {
;     ...
;     for (int ai = 0; ai < 2; ++ai)
; #pragma unroll
;       for (int m = 0; m < 4; ++m) {
;         const int row = u.pm * 256 + ai * HALF + wr * 64 + m * 16 + fr;
;         f32x4 sum = {0.f, 0.f, 0.f, 0.f};
; #pragma unroll
;         for (int bj = 0; bj < 2; ++bj)
; #pragma unroll
;           for (int n = 0; n < 2; ++n) {
;             const int br = 2 * bj + n;
;             const f32x4 v = acc[ai][bj][m][n] + bg[br];
;             const u32x2 z = zz[ai][m][br];
;             sum.x += sigm(v.x) * bflo(z.x); sum.y += sigm(v.y) * bfhi(z.x); sum.z += sigm(v.z) * bflo(z.y); sum.w += sigm(v.w) * bfhi(z.y);
;           }
;         u32x2 o; o.x = pk2(sum.x, sum.y); o.y = pk2(sum.z, sum.w);
;         *(u32x2*)(mixed + (size_t)row * DM + cc) = o;
	v_add_f32_e32 v69, 1.0, v71
	v_rcp_f32_e32 v71, v65
	v_mul_f32_e32 v65, 0xbfb8aa3b, v66
	v_exp_f32_e32 v65, v65
	v_add_f32_e32 v68, 1.0, v68
	v_rcp_f32_e32 v68, v68
	v_rcp_f32_e32 v69, v69
	v_add_f32_e32 v65, 1.0, v65
	v_lshlrev_b32_e32 v75, 16, v198
	v_lshlrev_b32_e32 v74, 16, v192
	v_rcp_f32_e32 v73, v65
	v_mul_f32_e32 v65, 0xbfb8aa3b, v67
	v_pk_mul_f32 v[68:69], v[68:69], v[74:75]
	v_exp_f32_e32 v65, v65
	v_add_f32_e32 v68, v82, v68
	v_add_f32_e32 v74, v68, v69
	v_and_b32_e32 v69, 0xffff0000, v198
	v_and_b32_e32 v68, 0xffff0000, v192
	v_pk_mul_f32 v[68:69], v[70:71], v[68:69]
	v_add_f32_e32 v65, 1.0, v65
	v_add_f32_e32 v66, v78, v68
	v_rcp_f32_e32 v64, v64
	v_add_f32_e32 v70, v66, v69
	v_lshlrev_b32_e32 v69, 16, v199
	v_lshlrev_b32_e32 v68, 16, v193
	v_rcp_f32_e32 v65, v65
	v_pk_mul_f32 v[66:67], v[72:73], v[68:69]
	v_pk_add_f32 v[60:61], v[60:61], v[100:101]
	v_add_f32_e32 v66, v76, v66
	v_add_f32_e32 v68, v66, v67
	v_and_b32_e32 v67, 0xffff0000, v199
	v_and_b32_e32 v66, 0xffff0000, v193
	v_pk_mul_f32 v[64:65], v[64:65], v[66:67]
	v_lshlrev_b64 v[66:67], 12, v[190:191]
	v_add_f32_e32 v64, v77, v64
	v_lshl_add_u64 v[66:67], s[10:11], 0, v[66:67]
	v_pk_add_f32 v[62:63], v[62:63], v[102:103]
	v_mul_f32_e32 v61, 0xbfb8aa3b, v61
	v_add_f32_e32 v65, v64, v65
	v_cvt_pk_bf16_f32 v64, v74, v70
	v_lshl_add_u64 v[66:67], v[66:67], 0, v[154:155]
	v_exp_f32_e32 v61, v61
	v_mul_f32_e32 v62, 0xbfb8aa3b, v62
	v_cvt_pk_bf16_f32 v65, v68, v65
	global_store_dwordx2 v[66:67], v[64:65], off
	v_exp_f32_e32 v64, v62
	v_add_f32_e32 v61, 1.0, v61
	v_pk_add_f32 v[56:57], v[56:57], v[96:97]
	v_rcp_f32_e32 v62, v61
	v_add_f32_e32 v61, 1.0, v64
	v_mul_f32_e32 v57, 0xbfb8aa3b, v57
	v_rcp_f32_e32 v64, v61
	v_mul_f32_e32 v61, 0xbfb8aa3b, v63
	v_mul_f32_e32 v56, 0xbfb8aa3b, v56
	v_exp_f32_e32 v57, v57
	v_exp_f32_e32 v61, v61
	v_exp_f32_e32 v63, v56
	v_mul_f32_e32 v60, 0xbfb8aa3b, v60
	v_exp_f32_e32 v60, v60
	v_pk_add_f32 v[58:59], v[58:59], v[98:99]
	v_add_f32_e32 v57, 1.0, v57
	v_add_f32_e32 v56, 1.0, v61
	v_add_f32_e32 v61, 1.0, v63
	v_rcp_f32_e32 v63, v57
	v_mul_f32_e32 v57, 0xbfb8aa3b, v58
	v_exp_f32_e32 v57, v57
	v_add_f32_e32 v60, 1.0, v60
	v_rcp_f32_e32 v60, v60
	v_rcp_f32_e32 v61, v61
	v_add_f32_e32 v57, 1.0, v57
	v_lshlrev_b32_e32 v67, 16, v194
	v_lshlrev_b32_e32 v66, 16, v196
	v_rcp_f32_e32 v65, v57
	v_mul_f32_e32 v57, 0xbfb8aa3b, v59
	v_pk_mul_f32 v[60:61], v[60:61], v[66:67]
	v_exp_f32_e32 v57, v57
	v_add_f32_e32 v60, 0, v60
	v_add_f32_e32 v66, v60, v61
	v_and_b32_e32 v61, 0xffff0000, v194
	v_and_b32_e32 v60, 0xffff0000, v196
	v_pk_mul_f32 v[60:61], v[62:63], v[60:61]
	v_add_f32_e32 v57, 1.0, v57
	v_add_f32_e32 v58, 0, v60
	v_rcp_f32_e32 v56, v56
	v_add_f32_e32 v62, v58, v61
	v_lshlrev_b32_e32 v61, 16, v195
	v_lshlrev_b32_e32 v60, 16, v197
	v_rcp_f32_e32 v57, v57
	v_pk_mul_f32 v[58:59], v[64:65], v[60:61]
	v_pk_add_f32 v[52:53], v[52:53], v[88:89]
	v_add_f32_e32 v58, 0, v58
	v_add_f32_e32 v60, v58, v59
	v_and_b32_e32 v59, 0xffff0000, v195
	v_and_b32_e32 v58, 0xffff0000, v197
	v_pk_mul_f32 v[56:57], v[56:57], v[58:59]
	v_pk_add_f32 v[54:55], v[54:55], v[90:91]
	v_mul_f32_e32 v53, 0xbfb8aa3b, v53
	v_add_f32_e32 v56, 0, v56
	v_exp_f32_e32 v53, v53
	v_mul_f32_e32 v54, 0xbfb8aa3b, v54
	v_add_f32_e32 v61, v56, v57
	v_exp_f32_e32 v56, v54
	v_add_f32_e32 v53, 1.0, v53
	v_pk_add_f32 v[48:49], v[48:49], v[84:85]
	v_rcp_f32_e32 v54, v53
	v_add_f32_e32 v53, 1.0, v56
	v_mul_f32_e32 v49, 0xbfb8aa3b, v49
	v_rcp_f32_e32 v56, v53
	v_mul_f32_e32 v53, 0xbfb8aa3b, v55
	v_mul_f32_e32 v48, 0xbfb8aa3b, v48
	v_exp_f32_e32 v49, v49
	v_exp_f32_e32 v53, v53
	v_exp_f32_e32 v55, v48
	v_mul_f32_e32 v52, 0xbfb8aa3b, v52
	v_exp_f32_e32 v52, v52
	v_pk_add_f32 v[50:51], v[50:51], v[86:87]
	v_add_f32_e32 v49, 1.0, v49
	v_add_f32_e32 v48, 1.0, v53
	v_add_f32_e32 v53, 1.0, v55
	v_rcp_f32_e32 v55, v49
	v_mul_f32_e32 v49, 0xbfb8aa3b, v50
	v_exp_f32_e32 v49, v49
	v_add_f32_e32 v52, 1.0, v52
	v_rcp_f32_e32 v52, v52
	v_rcp_f32_e32 v53, v53
	v_add_f32_e32 v49, 1.0, v49
	v_lshlrev_b32_e32 v59, 16, v188
	v_lshlrev_b32_e32 v58, 16, v186
	v_rcp_f32_e32 v57, v49
	v_mul_f32_e32 v49, 0xbfb8aa3b, v51
	v_pk_mul_f32 v[52:53], v[52:53], v[58:59]
	v_exp_f32_e32 v49, v49
	v_add_f32_e32 v52, v66, v52
	v_add_f32_e32 v58, v52, v53
	v_and_b32_e32 v53, 0xffff0000, v188
	v_and_b32_e32 v52, 0xffff0000, v186
	v_pk_mul_f32 v[52:53], v[54:55], v[52:53]
	v_add_f32_e32 v49, 1.0, v49
	v_add_f32_e32 v50, v62, v52
	v_rcp_f32_e32 v48, v48
	v_add_f32_e32 v54, v50, v53
	v_lshlrev_b32_e32 v53, 16, v189
	v_lshlrev_b32_e32 v52, 16, v187
	v_rcp_f32_e32 v49, v49
	v_pk_mul_f32 v[50:51], v[56:57], v[52:53]
	v_pk_add_f32 v[44:45], v[44:45], v[100:101]
	v_add_f32_e32 v50, v60, v50
	v_add_f32_e32 v52, v50, v51
	v_and_b32_e32 v51, 0xffff0000, v189
	v_and_b32_e32 v50, 0xffff0000, v187
	v_pk_mul_f32 v[48:49], v[48:49], v[50:51]
	v_lshlrev_b64 v[50:51], 12, v[184:185]
	v_add_f32_e32 v48, v61, v48
	v_lshl_add_u64 v[50:51], s[10:11], 0, v[50:51]
	v_pk_add_f32 v[46:47], v[46:47], v[102:103]
	v_mul_f32_e32 v45, 0xbfb8aa3b, v45
	v_add_f32_e32 v49, v48, v49
	v_cvt_pk_bf16_f32 v48, v58, v54
	v_lshl_add_u64 v[50:51], v[50:51], 0, v[154:155]
	v_exp_f32_e32 v45, v45
	v_mul_f32_e32 v46, 0xbfb8aa3b, v46
	v_cvt_pk_bf16_f32 v49, v52, v49
	global_store_dwordx2 v[50:51], v[48:49], off
	v_exp_f32_e32 v48, v46
	v_add_f32_e32 v45, 1.0, v45
	v_pk_add_f32 v[40:41], v[40:41], v[96:97]
	v_rcp_f32_e32 v46, v45
	v_add_f32_e32 v45, 1.0, v48
	v_mul_f32_e32 v41, 0xbfb8aa3b, v41
	v_rcp_f32_e32 v48, v45
	v_mul_f32_e32 v45, 0xbfb8aa3b, v47
	v_mul_f32_e32 v40, 0xbfb8aa3b, v40
	v_exp_f32_e32 v41, v41
	v_exp_f32_e32 v45, v45
	v_exp_f32_e32 v47, v40
	v_mul_f32_e32 v44, 0xbfb8aa3b, v44
; DI unsigned pk2(float lo, float hi) { unsigned r; asm("v_cvt_pk_bf16_f32 %0, %1, %2" : "=v"(r) : "v"(lo), "v"(hi)); return r; }
; DI float bflo(unsigned u) { return __uint_as_float(u << 16); }
; DI float bfhi(unsigned u) { return __uint_as_float(u & 0xffff0000u); }
; DI float sigm(float x) { return __builtin_amdgcn_rcpf(1.f + __expf(-x)); }
;   DI void epi(const Acc& acc, const Unit& u, int wr, int wc, int fr, int fq) const {
;     ...
;     for (int ai = 0; ai < 2; ++ai)
; #pragma unroll
;       for (int m = 0; m < 4; ++m) {
;         const int row = u.pm * 256 + ai * HALF + wr * 64 + m * 16 + fr;
;         f32x4 sum = {0.f, 0.f, 0.f, 0.f};
; #pragma unroll
;         for (int bj = 0; bj < 2; ++bj)
; #pragma unroll
;           for (int n = 0; n < 2; ++n) {
;             const int br = 2 * bj + n;
;             const f32x4 v = acc[ai][bj][m][n] + bg[br];
;             const u32x2 z = zz[ai][m][br];
;             sum.x += sigm(v.x) * bflo(z.x); sum.y += sigm(v.y) * bfhi(z.x); sum.z += sigm(v.z) * bflo(z.y); sum.w += sigm(v.w) * bfhi(z.y);
;           }
;         u32x2 o; o.x = pk2(sum.x, sum.y); o.y = pk2(sum.z, sum.w);
;         *(u32x2*)(mixed + (size_t)row * DM + cc) = o;
	v_exp_f32_e32 v44, v44
	v_pk_add_f32 v[42:43], v[42:43], v[98:99]
	v_add_f32_e32 v41, 1.0, v41
	v_add_f32_e32 v40, 1.0, v45
	v_add_f32_e32 v45, 1.0, v47
	v_rcp_f32_e32 v47, v41
	v_mul_f32_e32 v41, 0xbfb8aa3b, v42
	v_exp_f32_e32 v41, v41
	v_add_f32_e32 v44, 1.0, v44
	v_rcp_f32_e32 v44, v44
	v_rcp_f32_e32 v45, v45
	v_add_f32_e32 v41, 1.0, v41
	v_lshlrev_b32_e32 v51, 16, v180
	v_lshlrev_b32_e32 v50, 16, v182
	v_rcp_f32_e32 v49, v41
	v_mul_f32_e32 v41, 0xbfb8aa3b, v43
	v_pk_mul_f32 v[44:45], v[44:45], v[50:51]
	v_exp_f32_e32 v41, v41
	v_add_f32_e32 v44, 0, v44
	v_add_f32_e32 v50, v44, v45
	v_and_b32_e32 v45, 0xffff0000, v180
	v_and_b32_e32 v44, 0xffff0000, v182
	v_pk_mul_f32 v[44:45], v[46:47], v[44:45]
	v_add_f32_e32 v41, 1.0, v41
	v_add_f32_e32 v42, 0, v44
	v_rcp_f32_e32 v40, v40
	v_add_f32_e32 v46, v42, v45
	v_lshlrev_b32_e32 v45, 16, v181
	v_lshlrev_b32_e32 v44, 16, v183
	v_rcp_f32_e32 v41, v41
	v_pk_mul_f32 v[42:43], v[48:49], v[44:45]
	v_pk_add_f32 v[36:37], v[36:37], v[88:89]
	v_add_f32_e32 v42, 0, v42
	v_add_f32_e32 v44, v42, v43
	v_and_b32_e32 v43, 0xffff0000, v181
	v_and_b32_e32 v42, 0xffff0000, v183
	v_pk_mul_f32 v[40:41], v[40:41], v[42:43]
	v_pk_add_f32 v[38:39], v[38:39], v[90:91]
	v_mul_f32_e32 v37, 0xbfb8aa3b, v37
	v_add_f32_e32 v40, 0, v40
	v_exp_f32_e32 v37, v37
	v_mul_f32_e32 v38, 0xbfb8aa3b, v38
	v_add_f32_e32 v45, v40, v41
	v_exp_f32_e32 v40, v38
	v_add_f32_e32 v37, 1.0, v37
	v_pk_add_f32 v[32:33], v[32:33], v[84:85]
	v_rcp_f32_e32 v38, v37
	v_add_f32_e32 v37, 1.0, v40
	v_mul_f32_e32 v33, 0xbfb8aa3b, v33
	v_rcp_f32_e32 v40, v37
	v_mul_f32_e32 v37, 0xbfb8aa3b, v39
	v_mul_f32_e32 v32, 0xbfb8aa3b, v32
	v_exp_f32_e32 v33, v33
	v_exp_f32_e32 v37, v37
	v_exp_f32_e32 v39, v32
	v_mul_f32_e32 v36, 0xbfb8aa3b, v36
	v_exp_f32_e32 v36, v36
	v_pk_add_f32 v[34:35], v[34:35], v[86:87]
	v_add_f32_e32 v33, 1.0, v33
	v_add_f32_e32 v32, 1.0, v37
	v_add_f32_e32 v37, 1.0, v39
	v_rcp_f32_e32 v39, v33
	v_mul_f32_e32 v33, 0xbfb8aa3b, v34
	v_exp_f32_e32 v33, v33
	v_add_f32_e32 v36, 1.0, v36
	v_rcp_f32_e32 v36, v36
	v_rcp_f32_e32 v37, v37
	v_add_f32_e32 v33, 1.0, v33
	v_lshlrev_b32_e32 v43, 16, v178
	v_lshlrev_b32_e32 v42, 16, v176
	v_rcp_f32_e32 v41, v33
	v_mul_f32_e32 v33, 0xbfb8aa3b, v35
	v_pk_mul_f32 v[36:37], v[36:37], v[42:43]
	v_exp_f32_e32 v33, v33
	v_add_f32_e32 v36, v50, v36
	v_add_f32_e32 v42, v36, v37
	v_and_b32_e32 v37, 0xffff0000, v178
	v_and_b32_e32 v36, 0xffff0000, v176
	v_pk_mul_f32 v[36:37], v[38:39], v[36:37]
	v_add_f32_e32 v33, 1.0, v33
	v_add_f32_e32 v34, v46, v36
	v_rcp_f32_e32 v32, v32
	v_add_f32_e32 v38, v34, v37
	v_lshlrev_b32_e32 v37, 16, v179
	v_lshlrev_b32_e32 v36, 16, v177
	v_rcp_f32_e32 v33, v33
	v_pk_mul_f32 v[34:35], v[40:41], v[36:37]
	v_pk_add_f32 v[28:29], v[28:29], v[100:101]
	v_add_f32_e32 v34, v44, v34
	v_add_f32_e32 v36, v34, v35
	v_and_b32_e32 v35, 0xffff0000, v179
	v_and_b32_e32 v34, 0xffff0000, v177
	v_pk_mul_f32 v[32:33], v[32:33], v[34:35]
	v_lshlrev_b64 v[34:35], 12, v[174:175]
	v_add_f32_e32 v32, v45, v32
	v_lshl_add_u64 v[34:35], s[10:11], 0, v[34:35]
	v_pk_add_f32 v[30:31], v[30:31], v[102:103]
	v_mul_f32_e32 v29, 0xbfb8aa3b, v29
	v_add_f32_e32 v33, v32, v33
	v_cvt_pk_bf16_f32 v32, v42, v38
	v_lshl_add_u64 v[34:35], v[34:35], 0, v[154:155]
	v_exp_f32_e32 v29, v29
	v_mul_f32_e32 v30, 0xbfb8aa3b, v30
	v_cvt_pk_bf16_f32 v33, v36, v33
	global_store_dwordx2 v[34:35], v[32:33], off
	v_exp_f32_e32 v32, v30
	v_add_f32_e32 v29, 1.0, v29
	v_pk_add_f32 v[24:25], v[24:25], v[96:97]
	v_rcp_f32_e32 v30, v29
	v_add_f32_e32 v29, 1.0, v32
	v_mul_f32_e32 v25, 0xbfb8aa3b, v25
	v_rcp_f32_e32 v32, v29
	v_mul_f32_e32 v29, 0xbfb8aa3b, v31
	v_mul_f32_e32 v24, 0xbfb8aa3b, v24
	v_exp_f32_e32 v25, v25
	v_exp_f32_e32 v29, v29
	v_exp_f32_e32 v31, v24
	v_mul_f32_e32 v28, 0xbfb8aa3b, v28
	v_exp_f32_e32 v28, v28
	v_pk_add_f32 v[26:27], v[26:27], v[98:99]
	v_add_f32_e32 v25, 1.0, v25
	v_add_f32_e32 v24, 1.0, v29
	v_add_f32_e32 v29, 1.0, v31
	v_rcp_f32_e32 v31, v25
	v_mul_f32_e32 v25, 0xbfb8aa3b, v26
	v_exp_f32_e32 v25, v25
	v_add_f32_e32 v28, 1.0, v28
	v_rcp_f32_e32 v28, v28
	v_rcp_f32_e32 v29, v29
	v_add_f32_e32 v25, 1.0, v25
	v_lshlrev_b32_e32 v35, 16, v170
	s_waitcnt vmcnt(0)
; DI unsigned pk2(float lo, float hi) { unsigned r; asm("v_cvt_pk_bf16_f32 %0, %1, %2" : "=v"(r) : "v"(lo), "v"(hi)); return r; }
; DI float bflo(unsigned u) { return __uint_as_float(u << 16); }
; DI float bfhi(unsigned u) { return __uint_as_float(u & 0xffff0000u); }
; DI float sigm(float x) { return __builtin_amdgcn_rcpf(1.f + __expf(-x)); }
; #define G_WAIT_V(n) asm volatile("s_waitcnt vmcnt(" #n ")" ::: "memory")
; #define G_BAR __builtin_amdgcn_s_barrier()
; template <class J>
; DI void gemm_phase(LAS unsigned char* lds, const J& job) {
;     ...
;     if (!has_next) break;
; #pragma unroll
;     for (int a = 0; a < 2; ++a)
; #pragma unroll
;       for (int b = 0; b < 2; ++b)
; #pragma unroll
;         for (int m = 0; m < 4; ++m)
; #pragma unroll
;           for (int n = 0; n < 2; ++n) acc[a][b][m][n] = (f32x4){0.f, 0.f, 0.f, 0.f};
;     cur = nxt; cA = nA; cB = nB; ++ui;
;   }
;   G_WAIT_V(0);
;   if (wr == 0) G_BAR;
;   G_BAR;
;   DI void epi(const Acc& acc, const Unit& u, int wr, int wc, int fr, int fq) const {
;     ...
;     for (int ai = 0; ai < 2; ++ai)
; #pragma unroll
;       for (int m = 0; m < 4; ++m) {
;         const int row = u.pm * 256 + ai * HALF + wr * 64 + m * 16 + fr;
;         f32x4 sum = {0.f, 0.f, 0.f, 0.f};
; #pragma unroll
;         for (int bj = 0; bj < 2; ++bj)
; #pragma unroll
;           for (int n = 0; n < 2; ++n) {
;             const int br = 2 * bj + n;
;             const f32x4 v = acc[ai][bj][m][n] + bg[br];
;             const u32x2 z = zz[ai][m][br];
;             sum.x += sigm(v.x) * bflo(z.x); sum.y += sigm(v.y) * bfhi(z.x); sum.z += sigm(v.z) * bflo(z.y); sum.w += sigm(v.w) * bfhi(z.y);
;           }
;         u32x2 o; o.x = pk2(sum.x, sum.y); o.y = pk2(sum.z, sum.w);
;         *(u32x2*)(mixed + (size_t)row * DM + cc) = o;
	v_lshlrev_b32_e32 v34, 16, v172
	v_rcp_f32_e32 v33, v25
	v_mul_f32_e32 v25, 0xbfb8aa3b, v27
	v_pk_mul_f32 v[28:29], v[28:29], v[34:35]
	v_exp_f32_e32 v25, v25
	v_add_f32_e32 v28, 0, v28
	v_add_f32_e32 v34, v28, v29
	v_and_b32_e32 v29, 0xffff0000, v170
	v_and_b32_e32 v28, 0xffff0000, v172
	v_pk_mul_f32 v[28:29], v[30:31], v[28:29]
	v_add_f32_e32 v25, 1.0, v25
	v_add_f32_e32 v26, 0, v28
	v_rcp_f32_e32 v24, v24
	v_add_f32_e32 v30, v26, v29
	v_lshlrev_b32_e32 v29, 16, v171
	v_lshlrev_b32_e32 v28, 16, v173
	v_rcp_f32_e32 v25, v25
	v_pk_mul_f32 v[26:27], v[32:33], v[28:29]
	v_pk_add_f32 v[20:21], v[20:21], v[88:89]
	v_add_f32_e32 v26, 0, v26
	v_add_f32_e32 v28, v26, v27
	v_and_b32_e32 v27, 0xffff0000, v171
	v_and_b32_e32 v26, 0xffff0000, v173
	v_pk_mul_f32 v[24:25], v[24:25], v[26:27]
	v_pk_add_f32 v[22:23], v[22:23], v[90:91]
	v_mul_f32_e32 v21, 0xbfb8aa3b, v21
	v_add_f32_e32 v24, 0, v24
	v_exp_f32_e32 v21, v21
	v_mul_f32_e32 v22, 0xbfb8aa3b, v22
	v_add_f32_e32 v29, v24, v25
	v_exp_f32_e32 v24, v22
	v_add_f32_e32 v21, 1.0, v21
	v_pk_add_f32 v[16:17], v[16:17], v[84:85]
	v_rcp_f32_e32 v22, v21
	v_add_f32_e32 v21, 1.0, v24
	v_mul_f32_e32 v17, 0xbfb8aa3b, v17
	v_rcp_f32_e32 v24, v21
	v_mul_f32_e32 v21, 0xbfb8aa3b, v23
	v_mul_f32_e32 v16, 0xbfb8aa3b, v16
	v_exp_f32_e32 v17, v17
	v_exp_f32_e32 v21, v21
	v_exp_f32_e32 v23, v16
	v_mul_f32_e32 v20, 0xbfb8aa3b, v20
	v_exp_f32_e32 v20, v20
	v_pk_add_f32 v[18:19], v[18:19], v[86:87]
	v_add_f32_e32 v17, 1.0, v17
	v_add_f32_e32 v16, 1.0, v21
	v_add_f32_e32 v21, 1.0, v23
	v_rcp_f32_e32 v23, v17
	v_mul_f32_e32 v17, 0xbfb8aa3b, v18
	v_exp_f32_e32 v17, v17
	v_add_f32_e32 v20, 1.0, v20
	v_rcp_f32_e32 v20, v20
	v_rcp_f32_e32 v21, v21
	v_add_f32_e32 v17, 1.0, v17
	v_lshlrev_b32_e32 v27, 16, v168
	v_lshlrev_b32_e32 v26, 16, v166
	v_rcp_f32_e32 v25, v17
	v_mul_f32_e32 v17, 0xbfb8aa3b, v19
	v_pk_mul_f32 v[20:21], v[20:21], v[26:27]
	v_exp_f32_e32 v17, v17
	v_add_f32_e32 v20, v34, v20
	v_add_f32_e32 v26, v20, v21
	v_and_b32_e32 v21, 0xffff0000, v168
	v_and_b32_e32 v20, 0xffff0000, v166
	v_pk_mul_f32 v[20:21], v[22:23], v[20:21]
	v_add_f32_e32 v17, 1.0, v17
	v_add_f32_e32 v18, v30, v20
	v_rcp_f32_e32 v16, v16
	v_add_f32_e32 v22, v18, v21
	v_lshlrev_b32_e32 v21, 16, v169
	v_lshlrev_b32_e32 v20, 16, v167
	v_rcp_f32_e32 v17, v17
	v_pk_mul_f32 v[18:19], v[24:25], v[20:21]
	v_pk_add_f32 v[12:13], v[12:13], v[100:101]
	v_add_f32_e32 v18, v28, v18
	v_add_f32_e32 v20, v18, v19
	v_and_b32_e32 v19, 0xffff0000, v169
	v_and_b32_e32 v18, 0xffff0000, v167
	v_pk_mul_f32 v[16:17], v[16:17], v[18:19]
	v_lshlrev_b64 v[18:19], 12, v[164:165]
	v_add_f32_e32 v16, v29, v16
	v_lshl_add_u64 v[18:19], s[10:11], 0, v[18:19]
	v_pk_add_f32 v[14:15], v[14:15], v[102:103]
	v_mul_f32_e32 v13, 0xbfb8aa3b, v13
	v_add_f32_e32 v17, v16, v17
	v_cvt_pk_bf16_f32 v16, v26, v22
	v_lshl_add_u64 v[18:19], v[18:19], 0, v[154:155]
	v_exp_f32_e32 v13, v13
	v_mul_f32_e32 v14, 0xbfb8aa3b, v14
	v_cvt_pk_bf16_f32 v17, v20, v17
	global_store_dwordx2 v[18:19], v[16:17], off
	v_exp_f32_e32 v16, v14
	v_add_f32_e32 v13, 1.0, v13
	v_pk_add_f32 v[8:9], v[8:9], v[96:97]
	v_rcp_f32_e32 v14, v13
	v_add_f32_e32 v13, 1.0, v16
	v_mul_f32_e32 v9, 0xbfb8aa3b, v9
	v_rcp_f32_e32 v16, v13
	v_mul_f32_e32 v13, 0xbfb8aa3b, v15
	v_mul_f32_e32 v8, 0xbfb8aa3b, v8
	v_exp_f32_e32 v9, v9
	v_exp_f32_e32 v13, v13
	v_exp_f32_e32 v15, v8
	v_mul_f32_e32 v12, 0xbfb8aa3b, v12
	v_exp_f32_e32 v12, v12
	v_pk_add_f32 v[10:11], v[10:11], v[98:99]
	v_add_f32_e32 v9, 1.0, v9
	v_add_f32_e32 v8, 1.0, v13
	v_add_f32_e32 v13, 1.0, v15
	v_rcp_f32_e32 v15, v9
	v_mul_f32_e32 v9, 0xbfb8aa3b, v10
	v_exp_f32_e32 v9, v9
	v_add_f32_e32 v12, 1.0, v12
	v_rcp_f32_e32 v12, v12
	v_rcp_f32_e32 v13, v13
	v_add_f32_e32 v9, 1.0, v9
	v_lshlrev_b32_e32 v19, 16, v160
	v_lshlrev_b32_e32 v18, 16, v162
	v_rcp_f32_e32 v17, v9
	v_mul_f32_e32 v9, 0xbfb8aa3b, v11
	v_pk_mul_f32 v[12:13], v[12:13], v[18:19]
	v_exp_f32_e32 v9, v9
	v_add_f32_e32 v12, 0, v12
	v_add_f32_e32 v18, v12, v13
	v_and_b32_e32 v13, 0xffff0000, v160
	v_and_b32_e32 v12, 0xffff0000, v162
	v_pk_mul_f32 v[12:13], v[14:15], v[12:13]
	v_add_f32_e32 v9, 1.0, v9
	v_add_f32_e32 v10, 0, v12
	v_rcp_f32_e32 v8, v8
	v_add_f32_e32 v14, v10, v13
	v_lshlrev_b32_e32 v13, 16, v161
	v_lshlrev_b32_e32 v12, 16, v163
	v_rcp_f32_e32 v9, v9
	v_pk_mul_f32 v[10:11], v[16:17], v[12:13]
	v_pk_add_f32 v[4:5], v[4:5], v[88:89]
	v_add_f32_e32 v10, 0, v10
	v_add_f32_e32 v12, v10, v11
	v_and_b32_e32 v11, 0xffff0000, v161
	v_and_b32_e32 v10, 0xffff0000, v163
	v_pk_mul_f32 v[8:9], v[8:9], v[10:11]
	v_pk_add_f32 v[6:7], v[6:7], v[90:91]
	v_mul_f32_e32 v5, 0xbfb8aa3b, v5
	v_add_f32_e32 v8, 0, v8
	v_exp_f32_e32 v5, v5
	v_mul_f32_e32 v6, 0xbfb8aa3b, v6
	v_add_f32_e32 v13, v8, v9
	v_exp_f32_e32 v8, v6
	v_add_f32_e32 v5, 1.0, v5
	v_pk_add_f32 v[0:1], v[0:1], v[84:85]
	v_rcp_f32_e32 v6, v5
	v_add_f32_e32 v5, 1.0, v8
	v_mul_f32_e32 v1, 0xbfb8aa3b, v1
	v_rcp_f32_e32 v8, v5
	v_mul_f32_e32 v5, 0xbfb8aa3b, v7
	v_mul_f32_e32 v0, 0xbfb8aa3b, v0
	v_exp_f32_e32 v1, v1
	v_exp_f32_e32 v5, v5
	v_exp_f32_e32 v7, v0
	v_mul_f32_e32 v4, 0xbfb8aa3b, v4
	v_exp_f32_e32 v4, v4
	v_pk_add_f32 v[2:3], v[2:3], v[86:87]
	v_add_f32_e32 v1, 1.0, v1
	v_add_f32_e32 v0, 1.0, v5
	v_add_f32_e32 v5, 1.0, v7
	v_rcp_f32_e32 v7, v1
	v_mul_f32_e32 v1, 0xbfb8aa3b, v2
	v_exp_f32_e32 v1, v1
	v_add_f32_e32 v4, 1.0, v4
	v_rcp_f32_e32 v4, v4
	v_rcp_f32_e32 v5, v5
	v_add_f32_e32 v1, 1.0, v1
	v_lshlrev_b32_e32 v11, 16, v140
	v_lshlrev_b32_e32 v10, 16, v158
	v_rcp_f32_e32 v9, v1
	v_mul_f32_e32 v1, 0xbfb8aa3b, v3
	v_pk_mul_f32 v[4:5], v[4:5], v[10:11]
	v_exp_f32_e32 v1, v1
	v_add_f32_e32 v4, v18, v4
	v_add_f32_e32 v10, v4, v5
	v_and_b32_e32 v5, 0xffff0000, v140
	v_and_b32_e32 v4, 0xffff0000, v158
	v_pk_mul_f32 v[4:5], v[6:7], v[4:5]
	v_add_f32_e32 v1, 1.0, v1
	v_add_f32_e32 v2, v14, v4
	v_rcp_f32_e32 v0, v0
	v_add_f32_e32 v6, v2, v5
	v_lshlrev_b32_e32 v5, 16, v141
	v_lshlrev_b32_e32 v4, 16, v159
	v_rcp_f32_e32 v1, v1
	v_pk_mul_f32 v[2:3], v[8:9], v[4:5]
	s_nop 0
	v_add_f32_e32 v2, v12, v2
	v_add_f32_e32 v4, v2, v3
	v_and_b32_e32 v3, 0xffff0000, v141
	v_and_b32_e32 v2, 0xffff0000, v159
	v_pk_mul_f32 v[0:1], v[0:1], v[2:3]
	v_lshlrev_b64 v[2:3], 12, v[156:157]
	v_add_f32_e32 v0, v13, v0
	v_lshl_add_u64 v[2:3], s[10:11], 0, v[2:3]
	v_add_f32_e32 v1, v0, v1
	v_lshl_add_u64 v[2:3], v[2:3], 0, v[154:155]
	v_cvt_pk_bf16_f32 v0, v10, v6
	v_cvt_pk_bf16_f32 v1, v4, v1
	global_store_dwordx2 v[2:3], v[0:1], off
	s_cbranch_vccnz .Lds_gate_done
	v_readlane_b32 s0, v255, 23
	s_cmpk_gt_u32 s0, 0xff
	s_cbranch_scc0 .LBB0_67
	s_barrier
	s_branch .LBB0_67
